# baseline (speedup 1.0000x reference)
.LBB0_364:
	ds_read_b128 v[138:141], v137
	ds_read_b128 v[142:145], v137 offset:1024
	ds_read_b128 v[146:149], v137 offset:2048
	ds_read_b128 v[150:153], v137 offset:3072
	s_add_u32 s64, s20, s18
	s_addc_u32 s65, s21, s19
	s_add_u32 s62, s64, 0x180
	s_addc_u32 s63, s65, 0
	s_mov_b32 m0, s42
	ds_read_b128 v[154:157], v136
	ds_read_b128 v[158:161], v136 offset:1024
	ds_read_b128 v[162:165], v136 offset:2048
	ds_read_b128 v[166:169], v136 offset:3072
	ds_read_b128 v[170:173], v136 offset:4096
	ds_read_b128 v[174:177], v136 offset:5120
	ds_read_b128 v[178:181], v136 offset:6144
	ds_read_b128 v[182:185], v136 offset:7168
	ds_read_b128 v[186:189], v137 offset:16384
	ds_read_b128 v[190:193], v137 offset:17408
	ds_read_b128 v[194:197], v137 offset:18432
	ds_read_b128 v[198:201], v137 offset:19456
	s_nop 0
	global_load_lds_dwordx4 v130, s[62:63]
	s_mov_b32 m0, s43
	s_nop 0
	global_load_lds_dwordx4 v132, s[62:63]
	s_waitcnt vmcnt(8)
	s_waitcnt lgkmcnt(0)
	s_barrier
	s_setprio 3
	v_mfma_f32_16x16x32_bf16 v[30:33], v[154:157], v[138:141], v[30:33]
	v_mfma_f32_16x16x32_bf16 v[26:29], v[154:157], v[146:149], v[26:29]
	v_mfma_f32_16x16x32_bf16 v[22:25], v[162:165], v[138:141], v[22:25]
	v_mfma_f32_16x16x32_bf16 v[18:21], v[162:165], v[146:149], v[18:21]
	v_mfma_f32_16x16x32_bf16 v[14:17], v[170:173], v[138:141], v[14:17]
	v_mfma_f32_16x16x32_bf16 v[10:13], v[170:173], v[146:149], v[10:13]
	v_mfma_f32_16x16x32_bf16 v[6:9], v[178:181], v[138:141], v[6:9]
	v_mfma_f32_16x16x32_bf16 v[2:5], v[178:181], v[146:149], v[2:5]
	v_mfma_f32_16x16x32_bf16 v[30:33], v[158:161], v[142:145], v[30:33]
	v_mfma_f32_16x16x32_bf16 v[26:29], v[158:161], v[150:153], v[26:29]
	v_mfma_f32_16x16x32_bf16 v[22:25], v[166:169], v[142:145], v[22:25]
	v_mfma_f32_16x16x32_bf16 v[18:21], v[166:169], v[150:153], v[18:21]
	v_mfma_f32_16x16x32_bf16 v[14:17], v[174:177], v[142:145], v[14:17]
	v_mfma_f32_16x16x32_bf16 v[10:13], v[174:177], v[150:153], v[10:13]
	v_mfma_f32_16x16x32_bf16 v[6:9], v[182:185], v[142:145], v[6:9]
	v_mfma_f32_16x16x32_bf16 v[2:5], v[182:185], v[150:153], v[2:5]
	v_mfma_f32_16x16x32_bf16 v[62:65], v[154:157], v[186:189], v[62:65]
	v_mfma_f32_16x16x32_bf16 v[58:61], v[154:157], v[194:197], v[58:61]
	v_mfma_f32_16x16x32_bf16 v[54:57], v[162:165], v[186:189], v[54:57]
	v_mfma_f32_16x16x32_bf16 v[50:53], v[162:165], v[194:197], v[50:53]
	v_mfma_f32_16x16x32_bf16 v[46:49], v[170:173], v[186:189], v[46:49]
	v_mfma_f32_16x16x32_bf16 v[42:45], v[170:173], v[194:197], v[42:45]
	v_mfma_f32_16x16x32_bf16 v[38:41], v[178:181], v[186:189], v[38:41]
	v_mfma_f32_16x16x32_bf16 v[34:37], v[178:181], v[194:197], v[34:37]
	v_mfma_f32_16x16x32_bf16 v[62:65], v[158:161], v[190:193], v[62:65]
	v_mfma_f32_16x16x32_bf16 v[58:61], v[158:161], v[198:201], v[58:61]
	v_mfma_f32_16x16x32_bf16 v[54:57], v[166:169], v[190:193], v[54:57]
	v_mfma_f32_16x16x32_bf16 v[50:53], v[166:169], v[198:201], v[50:53]
	v_mfma_f32_16x16x32_bf16 v[46:49], v[174:177], v[190:193], v[46:49]
	v_mfma_f32_16x16x32_bf16 v[42:45], v[174:177], v[198:201], v[42:45]
	v_mfma_f32_16x16x32_bf16 v[38:41], v[182:185], v[190:193], v[38:41]
	v_mfma_f32_16x16x32_bf16 v[34:37], v[182:185], v[198:201], v[34:37]
	s_setprio 0
	s_barrier
	ds_read_b128 v[154:157], v136 offset:16384
	ds_read_b128 v[158:161], v136 offset:17408
	ds_read_b128 v[162:165], v136 offset:18432
	ds_read_b128 v[166:169], v136 offset:19456
	ds_read_b128 v[170:173], v136 offset:20480
	ds_read_b128 v[174:177], v136 offset:21504
	ds_read_b128 v[178:181], v136 offset:22528
	ds_read_b128 v[182:185], v136 offset:23552
	s_add_u32 s66, s56, s18
	s_addc_u32 s67, s57, s19
	s_add_u32 s62, s66, 0x200
	s_addc_u32 s63, s67, 0
	s_mov_b32 m0, s28
	s_nop 0
	global_load_lds_dwordx4 v130, s[62:63]
	s_mov_b32 m0, s29
	s_nop 0
	global_load_lds_dwordx4 v132, s[62:63]
	s_add_u32 s68, s17, s18
	s_addc_u32 s69, s58, s19
	s_add_u32 s62, s68, 0x200
	s_addc_u32 s63, s69, 0
	s_mov_b32 m0, s27
	s_nop 0
	global_load_lds_dwordx4 v130, s[62:63]
	s_mov_b32 m0, s30
	s_nop 0
	global_load_lds_dwordx4 v132, s[62:63]
	s_add_u32 s70, s59, s18
	s_addc_u32 s71, s60, s19
	s_add_u32 s62, s70, 0x200
	s_addc_u32 s63, s71, 0
	s_mov_b32 m0, s31
	s_nop 0
	global_load_lds_dwordx4 v130, s[62:63]
	s_mov_b32 m0, s33
	s_nop 0
	global_load_lds_dwordx4 v132, s[62:63]
	s_waitcnt vmcnt(8)
	s_waitcnt lgkmcnt(0)
	s_barrier
	s_setprio 3
	v_mfma_f32_16x16x32_bf16 v[94:97], v[154:157], v[138:141], v[94:97]
	v_mfma_f32_16x16x32_bf16 v[90:93], v[154:157], v[146:149], v[90:93]
	v_mfma_f32_16x16x32_bf16 v[86:89], v[162:165], v[138:141], v[86:89]
	v_mfma_f32_16x16x32_bf16 v[82:85], v[162:165], v[146:149], v[82:85]
	v_mfma_f32_16x16x32_bf16 v[78:81], v[170:173], v[138:141], v[78:81]
	v_mfma_f32_16x16x32_bf16 v[74:77], v[170:173], v[146:149], v[74:77]
	v_mfma_f32_16x16x32_bf16 v[70:73], v[178:181], v[138:141], v[70:73]
	v_mfma_f32_16x16x32_bf16 v[66:69], v[178:181], v[146:149], v[66:69]
	v_mfma_f32_16x16x32_bf16 v[94:97], v[158:161], v[142:145], v[94:97]
	v_mfma_f32_16x16x32_bf16 v[90:93], v[158:161], v[150:153], v[90:93]
	v_mfma_f32_16x16x32_bf16 v[86:89], v[166:169], v[142:145], v[86:89]
	v_mfma_f32_16x16x32_bf16 v[82:85], v[166:169], v[150:153], v[82:85]
	v_mfma_f32_16x16x32_bf16 v[78:81], v[174:177], v[142:145], v[78:81]
	v_mfma_f32_16x16x32_bf16 v[74:77], v[174:177], v[150:153], v[74:77]
	v_mfma_f32_16x16x32_bf16 v[70:73], v[182:185], v[142:145], v[70:73]
	v_mfma_f32_16x16x32_bf16 v[66:69], v[182:185], v[150:153], v[66:69]
	v_mfma_f32_16x16x32_bf16 v[126:129], v[154:157], v[186:189], v[126:129]
	v_mfma_f32_16x16x32_bf16 v[122:125], v[154:157], v[194:197], v[122:125]
	v_mfma_f32_16x16x32_bf16 v[118:121], v[162:165], v[186:189], v[118:121]
	v_mfma_f32_16x16x32_bf16 v[114:117], v[162:165], v[194:197], v[114:117]
	v_mfma_f32_16x16x32_bf16 v[110:113], v[170:173], v[186:189], v[110:113]
	v_mfma_f32_16x16x32_bf16 v[106:109], v[170:173], v[194:197], v[106:109]
	v_mfma_f32_16x16x32_bf16 v[102:105], v[178:181], v[186:189], v[102:105]
	v_mfma_f32_16x16x32_bf16 v[98:101], v[178:181], v[194:197], v[98:101]
	v_mfma_f32_16x16x32_bf16 v[126:129], v[158:161], v[190:193], v[126:129]
	v_mfma_f32_16x16x32_bf16 v[122:125], v[158:161], v[198:201], v[122:125]
	v_mfma_f32_16x16x32_bf16 v[118:121], v[166:169], v[190:193], v[118:121]
	v_mfma_f32_16x16x32_bf16 v[114:117], v[166:169], v[198:201], v[114:117]
	v_mfma_f32_16x16x32_bf16 v[110:113], v[174:177], v[190:193], v[110:113]
	v_mfma_f32_16x16x32_bf16 v[106:109], v[174:177], v[198:201], v[106:109]
	v_mfma_f32_16x16x32_bf16 v[102:105], v[182:185], v[190:193], v[102:105]
	v_mfma_f32_16x16x32_bf16 v[98:101], v[182:185], v[198:201], v[98:101]
	s_setprio 0
	s_barrier
	ds_read_b128 v[138:141], v137 offset:32768
	ds_read_b128 v[142:145], v137 offset:33792
	ds_read_b128 v[146:149], v137 offset:34816
	ds_read_b128 v[150:153], v137 offset:35840
	s_add_u32 s62, s64, 0x200
	s_addc_u32 s63, s65, 0
	s_mov_b32 m0, s34
	ds_read_b128 v[154:157], v136 offset:32768
	ds_read_b128 v[158:161], v136 offset:33792
	ds_read_b128 v[162:165], v136 offset:34816
	ds_read_b128 v[166:169], v136 offset:35840
	ds_read_b128 v[170:173], v136 offset:36864
	ds_read_b128 v[174:177], v136 offset:37888
	ds_read_b128 v[178:181], v136 offset:38912
	ds_read_b128 v[182:185], v136 offset:39936
	ds_read_b128 v[186:189], v137 offset:49152
	ds_read_b128 v[190:193], v137 offset:50176
	ds_read_b128 v[194:197], v137 offset:51200
	ds_read_b128 v[198:201], v137 offset:52224
	s_nop 0
	global_load_lds_dwordx4 v130, s[62:63]
	s_mov_b32 m0, s35
	s_nop 0
	global_load_lds_dwordx4 v132, s[62:63]
	s_waitcnt vmcnt(8)
	s_waitcnt lgkmcnt(0)
	s_barrier
	s_setprio 3
	v_mfma_f32_16x16x32_bf16 v[30:33], v[154:157], v[138:141], v[30:33]
	v_mfma_f32_16x16x32_bf16 v[26:29], v[154:157], v[146:149], v[26:29]
	v_mfma_f32_16x16x32_bf16 v[22:25], v[162:165], v[138:141], v[22:25]
	v_mfma_f32_16x16x32_bf16 v[18:21], v[162:165], v[146:149], v[18:21]
	v_mfma_f32_16x16x32_bf16 v[14:17], v[170:173], v[138:141], v[14:17]
	v_mfma_f32_16x16x32_bf16 v[10:13], v[170:173], v[146:149], v[10:13]
	v_mfma_f32_16x16x32_bf16 v[6:9], v[178:181], v[138:141], v[6:9]
	v_mfma_f32_16x16x32_bf16 v[2:5], v[178:181], v[146:149], v[2:5]
	v_mfma_f32_16x16x32_bf16 v[30:33], v[158:161], v[142:145], v[30:33]
	v_mfma_f32_16x16x32_bf16 v[26:29], v[158:161], v[150:153], v[26:29]
	v_mfma_f32_16x16x32_bf16 v[22:25], v[166:169], v[142:145], v[22:25]
	v_mfma_f32_16x16x32_bf16 v[18:21], v[166:169], v[150:153], v[18:21]
	v_mfma_f32_16x16x32_bf16 v[14:17], v[174:177], v[142:145], v[14:17]
	v_mfma_f32_16x16x32_bf16 v[10:13], v[174:177], v[150:153], v[10:13]
	v_mfma_f32_16x16x32_bf16 v[6:9], v[182:185], v[142:145], v[6:9]
	v_mfma_f32_16x16x32_bf16 v[2:5], v[182:185], v[150:153], v[2:5]
	v_mfma_f32_16x16x32_bf16 v[62:65], v[154:157], v[186:189], v[62:65]
	v_mfma_f32_16x16x32_bf16 v[58:61], v[154:157], v[194:197], v[58:61]
	v_mfma_f32_16x16x32_bf16 v[54:57], v[162:165], v[186:189], v[54:57]
	v_mfma_f32_16x16x32_bf16 v[50:53], v[162:165], v[194:197], v[50:53]
	v_mfma_f32_16x16x32_bf16 v[46:49], v[170:173], v[186:189], v[46:49]
	v_mfma_f32_16x16x32_bf16 v[42:45], v[170:173], v[194:197], v[42:45]
	v_mfma_f32_16x16x32_bf16 v[38:41], v[178:181], v[186:189], v[38:41]
	v_mfma_f32_16x16x32_bf16 v[34:37], v[178:181], v[194:197], v[34:37]
	v_mfma_f32_16x16x32_bf16 v[62:65], v[158:161], v[190:193], v[62:65]
	v_mfma_f32_16x16x32_bf16 v[58:61], v[158:161], v[198:201], v[58:61]
	v_mfma_f32_16x16x32_bf16 v[54:57], v[166:169], v[190:193], v[54:57]
	v_mfma_f32_16x16x32_bf16 v[50:53], v[166:169], v[198:201], v[50:53]
	v_mfma_f32_16x16x32_bf16 v[46:49], v[174:177], v[190:193], v[46:49]
	v_mfma_f32_16x16x32_bf16 v[42:45], v[174:177], v[198:201], v[42:45]
	v_mfma_f32_16x16x32_bf16 v[38:41], v[182:185], v[190:193], v[38:41]
	v_mfma_f32_16x16x32_bf16 v[34:37], v[182:185], v[198:201], v[34:37]
	s_setprio 0
	s_barrier
	ds_read_b128 v[154:157], v136 offset:49152
	ds_read_b128 v[158:161], v136 offset:50176
	ds_read_b128 v[162:165], v136 offset:51200
	ds_read_b128 v[166:169], v136 offset:52224
	ds_read_b128 v[170:173], v136 offset:53248
	ds_read_b128 v[174:177], v136 offset:54272
	ds_read_b128 v[178:181], v136 offset:55296
	ds_read_b128 v[182:185], v136 offset:56320
	s_add_u32 s62, s66, 0x280
	s_addc_u32 s63, s67, 0
	s_mov_b32 m0, s36
	s_nop 0
	global_load_lds_dwordx4 v130, s[62:63]
	s_mov_b32 m0, s37
	s_nop 0
	global_load_lds_dwordx4 v132, s[62:63]
	s_add_u32 s62, s68, 0x280
	s_addc_u32 s63, s69, 0
	s_mov_b32 m0, s38
	s_nop 0
	global_load_lds_dwordx4 v130, s[62:63]
	s_mov_b32 m0, s39
	s_nop 0
	global_load_lds_dwordx4 v132, s[62:63]
	s_add_u32 s62, s70, 0x280
	s_addc_u32 s63, s71, 0
	s_mov_b32 m0, s40
	s_nop 0
	global_load_lds_dwordx4 v130, s[62:63]
	s_mov_b32 m0, s41
	s_nop 0
	global_load_lds_dwordx4 v132, s[62:63]
	s_waitcnt vmcnt(8)
	s_waitcnt lgkmcnt(0)
	s_barrier
	s_setprio 3
	v_mfma_f32_16x16x32_bf16 v[94:97], v[154:157], v[138:141], v[94:97]
	v_mfma_f32_16x16x32_bf16 v[90:93], v[154:157], v[146:149], v[90:93]
	v_mfma_f32_16x16x32_bf16 v[86:89], v[162:165], v[138:141], v[86:89]
	v_mfma_f32_16x16x32_bf16 v[82:85], v[162:165], v[146:149], v[82:85]
	v_mfma_f32_16x16x32_bf16 v[78:81], v[170:173], v[138:141], v[78:81]
	v_mfma_f32_16x16x32_bf16 v[74:77], v[170:173], v[146:149], v[74:77]
	v_mfma_f32_16x16x32_bf16 v[70:73], v[178:181], v[138:141], v[70:73]
	v_mfma_f32_16x16x32_bf16 v[66:69], v[178:181], v[146:149], v[66:69]
	v_mfma_f32_16x16x32_bf16 v[94:97], v[158:161], v[142:145], v[94:97]
	v_mfma_f32_16x16x32_bf16 v[90:93], v[158:161], v[150:153], v[90:93]
	v_mfma_f32_16x16x32_bf16 v[86:89], v[166:169], v[142:145], v[86:89]
	v_mfma_f32_16x16x32_bf16 v[82:85], v[166:169], v[150:153], v[82:85]
	v_mfma_f32_16x16x32_bf16 v[78:81], v[174:177], v[142:145], v[78:81]
	v_mfma_f32_16x16x32_bf16 v[74:77], v[174:177], v[150:153], v[74:77]
	v_mfma_f32_16x16x32_bf16 v[70:73], v[182:185], v[142:145], v[70:73]
	v_mfma_f32_16x16x32_bf16 v[66:69], v[182:185], v[150:153], v[66:69]
	v_mfma_f32_16x16x32_bf16 v[126:129], v[154:157], v[186:189], v[126:129]
	v_mfma_f32_16x16x32_bf16 v[122:125], v[154:157], v[194:197], v[122:125]
	v_mfma_f32_16x16x32_bf16 v[118:121], v[162:165], v[186:189], v[118:121]
	v_mfma_f32_16x16x32_bf16 v[114:117], v[162:165], v[194:197], v[114:117]
	v_mfma_f32_16x16x32_bf16 v[110:113], v[170:173], v[186:189], v[110:113]
	v_mfma_f32_16x16x32_bf16 v[106:109], v[170:173], v[194:197], v[106:109]
	v_mfma_f32_16x16x32_bf16 v[102:105], v[178:181], v[186:189], v[102:105]
	v_mfma_f32_16x16x32_bf16 v[98:101], v[178:181], v[194:197], v[98:101]
	v_mfma_f32_16x16x32_bf16 v[126:129], v[158:161], v[190:193], v[126:129]
	v_mfma_f32_16x16x32_bf16 v[122:125], v[158:161], v[198:201], v[122:125]
	v_mfma_f32_16x16x32_bf16 v[118:121], v[166:169], v[190:193], v[118:121]
	v_mfma_f32_16x16x32_bf16 v[114:117], v[166:169], v[198:201], v[114:117]
	v_mfma_f32_16x16x32_bf16 v[110:113], v[174:177], v[190:193], v[110:113]
	v_mfma_f32_16x16x32_bf16 v[106:109], v[174:177], v[198:201], v[106:109]
	v_mfma_f32_16x16x32_bf16 v[102:105], v[182:185], v[190:193], v[102:105]
	v_mfma_f32_16x16x32_bf16 v[98:101], v[182:185], v[198:201], v[98:101]
	s_setprio 0
	s_add_i32 s61, s61, 2
	s_add_u32 s18, s18, 0x100
	s_addc_u32 s19, s19, 0
	s_cmp_gt_u32 s61, 11
	s_barrier
	s_cbranch_scc0 .LBB0_364
	s_lshl_b64 s[14:15], s[14:15], 1
	s_add_u32 s14, s44, s14
	s_addc_u32 s15, s45, s15
	s_mov_b32 m0, s42
	ds_read_b128 v[142:145], v137
	ds_read_b128 v[146:149], v137 offset:1024
	ds_read_b128 v[150:153], v137 offset:2048
	ds_read_b128 v[154:157], v137 offset:3072
	ds_read_b128 v[158:161], v136
	ds_read_b128 v[162:165], v136 offset:1024
	ds_read_b128 v[166:169], v136 offset:2048
	ds_read_b128 v[170:173], v136 offset:3072
	ds_read_b128 v[174:177], v136 offset:4096
	ds_read_b128 v[178:181], v136 offset:5120
	ds_read_b128 v[182:185], v136 offset:6144
	ds_read_b128 v[186:189], v136 offset:7168
	s_nop 0
	global_load_lds_dwordx4 v130, s[14:15]
	s_mov_b32 m0, s43
	s_nop 0
	global_load_lds_dwordx4 v132, s[14:15]
	s_waitcnt vmcnt(8)
	s_barrier
	s_waitcnt lgkmcnt(0)
	s_setprio 3
	s_waitcnt lgkmcnt(0)
	v_mfma_f32_16x16x32_bf16 v[30:33], v[158:161], v[142:145], v[30:33]
	v_mfma_f32_16x16x32_bf16 v[26:29], v[158:161], v[150:153], v[26:29]
	v_mfma_f32_16x16x32_bf16 v[22:25], v[166:169], v[142:145], v[22:25]
	v_mfma_f32_16x16x32_bf16 v[18:21], v[166:169], v[150:153], v[18:21]
	v_mfma_f32_16x16x32_bf16 v[14:17], v[174:177], v[142:145], v[14:17]
	v_mfma_f32_16x16x32_bf16 v[10:13], v[174:177], v[150:153], v[10:13]
	v_mfma_f32_16x16x32_bf16 v[6:9], v[182:185], v[142:145], v[6:9]
	v_mfma_f32_16x16x32_bf16 v[2:5], v[182:185], v[150:153], v[2:5]
	v_mfma_f32_16x16x32_bf16 v[30:33], v[162:165], v[146:149], v[30:33]
	v_mfma_f32_16x16x32_bf16 v[26:29], v[162:165], v[154:157], v[26:29]
	v_mfma_f32_16x16x32_bf16 v[22:25], v[170:173], v[146:149], v[22:25]
	v_mfma_f32_16x16x32_bf16 v[18:21], v[170:173], v[154:157], v[18:21]
	v_mfma_f32_16x16x32_bf16 v[14:17], v[178:181], v[146:149], v[14:17]
	v_mfma_f32_16x16x32_bf16 v[10:13], v[178:181], v[154:157], v[10:13]
	v_mfma_f32_16x16x32_bf16 v[6:9], v[186:189], v[146:149], v[6:9]
	v_mfma_f32_16x16x32_bf16 v[2:5], v[186:189], v[154:157], v[2:5]
	s_setprio 0
	s_barrier
	ds_read_b128 v[190:193], v137 offset:16384
	ds_read_b128 v[194:197], v137 offset:17408
	ds_read_b128 v[198:201], v137 offset:18432
	ds_read_b128 v[202:205], v137 offset:19456
	s_barrier
	s_waitcnt lgkmcnt(0)
	s_setprio 3
	s_waitcnt lgkmcnt(0)
	v_mfma_f32_16x16x32_bf16 v[62:65], v[158:161], v[190:193], v[62:65]
	v_mfma_f32_16x16x32_bf16 v[58:61], v[158:161], v[198:201], v[58:61]
	v_mfma_f32_16x16x32_bf16 v[54:57], v[166:169], v[190:193], v[54:57]
	v_mfma_f32_16x16x32_bf16 v[50:53], v[166:169], v[198:201], v[50:53]
	v_mfma_f32_16x16x32_bf16 v[46:49], v[174:177], v[190:193], v[46:49]
	v_mfma_f32_16x16x32_bf16 v[42:45], v[174:177], v[198:201], v[42:45]
	v_mfma_f32_16x16x32_bf16 v[38:41], v[182:185], v[190:193], v[38:41]
	v_mfma_f32_16x16x32_bf16 v[34:37], v[182:185], v[198:201], v[34:37]
	v_mfma_f32_16x16x32_bf16 v[62:65], v[162:165], v[194:197], v[62:65]
	v_mfma_f32_16x16x32_bf16 v[58:61], v[162:165], v[202:205], v[58:61]
	v_mfma_f32_16x16x32_bf16 v[54:57], v[170:173], v[194:197], v[54:57]
	v_mfma_f32_16x16x32_bf16 v[50:53], v[170:173], v[202:205], v[50:53]
	v_mfma_f32_16x16x32_bf16 v[46:49], v[178:181], v[194:197], v[46:49]
	v_mfma_f32_16x16x32_bf16 v[42:45], v[178:181], v[202:205], v[42:45]
	v_mfma_f32_16x16x32_bf16 v[38:41], v[186:189], v[194:197], v[38:41]
	v_mfma_f32_16x16x32_bf16 v[34:37], v[186:189], v[202:205], v[34:37]
	s_setprio 0
	s_barrier
	ds_read_b128 v[158:161], v136 offset:16384
	ds_read_b128 v[162:165], v136 offset:17408
	ds_read_b128 v[166:169], v136 offset:18432
	ds_read_b128 v[170:173], v136 offset:19456
	ds_read_b128 v[174:177], v136 offset:20480
	ds_read_b128 v[178:181], v136 offset:21504
	ds_read_b128 v[182:185], v136 offset:22528
	ds_read_b128 v[186:189], v136 offset:23552
	s_waitcnt vmcnt(4)
	s_barrier
	s_waitcnt lgkmcnt(0)
	s_setprio 3
	s_waitcnt lgkmcnt(0)
	v_mfma_f32_16x16x32_bf16 v[94:97], v[158:161], v[142:145], v[94:97]
	v_mfma_f32_16x16x32_bf16 v[90:93], v[158:161], v[150:153], v[90:93]
	v_mfma_f32_16x16x32_bf16 v[86:89], v[166:169], v[142:145], v[86:89]
	v_mfma_f32_16x16x32_bf16 v[82:85], v[166:169], v[150:153], v[82:85]
	v_mfma_f32_16x16x32_bf16 v[78:81], v[174:177], v[142:145], v[78:81]
	v_mfma_f32_16x16x32_bf16 v[74:77], v[174:177], v[150:153], v[74:77]
	v_mfma_f32_16x16x32_bf16 v[70:73], v[182:185], v[142:145], v[70:73]
	v_mfma_f32_16x16x32_bf16 v[66:69], v[182:185], v[150:153], v[66:69]
	v_mfma_f32_16x16x32_bf16 v[212:215], v[162:165], v[146:149], v[94:97]
	v_mfma_f32_16x16x32_bf16 v[216:219], v[162:165], v[154:157], v[90:93]
	v_mfma_f32_16x16x32_bf16 v[220:223], v[170:173], v[146:149], v[86:89]
	v_mfma_f32_16x16x32_bf16 v[224:227], v[170:173], v[154:157], v[82:85]
	v_mfma_f32_16x16x32_bf16 v[228:231], v[178:181], v[146:149], v[78:81]
	v_mfma_f32_16x16x32_bf16 v[232:235], v[178:181], v[154:157], v[74:77]
	v_mfma_f32_16x16x32_bf16 v[142:145], v[186:189], v[146:149], v[70:73]
	v_mfma_f32_16x16x32_bf16 v[146:149], v[186:189], v[154:157], v[66:69]
	s_setprio 0
	s_setprio 3
	v_mfma_f32_16x16x32_bf16 v[66:69], v[158:161], v[190:193], v[126:129]
	v_mfma_f32_16x16x32_bf16 v[150:153], v[162:165], v[194:197], v[66:69]
	v_mfma_f32_16x16x32_bf16 v[66:69], v[158:161], v[198:201], v[122:125]
	v_mfma_f32_16x16x32_bf16 v[154:157], v[162:165], v[202:205], v[66:69]
	v_mfma_f32_16x16x32_bf16 v[66:69], v[166:169], v[190:193], v[118:121]
	v_mfma_f32_16x16x32_bf16 v[158:161], v[170:173], v[194:197], v[66:69]
	v_mfma_f32_16x16x32_bf16 v[66:69], v[166:169], v[198:201], v[114:117]
	v_mfma_f32_16x16x32_bf16 v[162:165], v[170:173], v[202:205], v[66:69]
	v_mfma_f32_16x16x32_bf16 v[66:69], v[174:177], v[190:193], v[110:113]
	v_mfma_f32_16x16x32_bf16 v[166:169], v[178:181], v[194:197], v[66:69]
	v_mfma_f32_16x16x32_bf16 v[66:69], v[174:177], v[198:201], v[106:109]
	v_mfma_f32_16x16x32_bf16 v[170:173], v[178:181], v[202:205], v[66:69]
	v_mfma_f32_16x16x32_bf16 v[66:69], v[182:185], v[190:193], v[102:105]
	v_mfma_f32_16x16x32_bf16 v[174:177], v[186:189], v[194:197], v[66:69]
	v_mfma_f32_16x16x32_bf16 v[66:69], v[182:185], v[198:201], v[98:101]
	v_mfma_f32_16x16x32_bf16 v[178:181], v[186:189], v[202:205], v[66:69]
	s_setprio 0
	s_barrier
	ds_read_b128 v[182:185], v137 offset:32768
	ds_read_b128 v[186:189], v137 offset:33792
	ds_read_b128 v[190:193], v137 offset:34816
	ds_read_b128 v[194:197], v137 offset:35840
	s_nop 0
	ds_read_b128 v[66:69], v136 offset:32768
	ds_read_b128 v[70:73], v136 offset:33792
	ds_read_b128 v[82:85], v136 offset:34816
	ds_read_b128 v[86:89], v136 offset:35840
	ds_read_b128 v[198:201], v136 offset:36864
	ds_read_b128 v[202:205], v136 offset:37888
	ds_read_b128 v[236:239], v136 offset:38912
	ds_read_b128 v[240:243], v136 offset:39936
	s_waitcnt vmcnt(2)
	s_barrier
	s_waitcnt lgkmcnt(0)
	s_setprio 3
	s_waitcnt lgkmcnt(0)
	v_mfma_f32_16x16x32_bf16 v[30:33], v[66:69], v[182:185], v[30:33]
	v_mfma_f32_16x16x32_bf16 v[26:29], v[66:69], v[190:193], v[26:29]
	v_mfma_f32_16x16x32_bf16 v[22:25], v[82:85], v[182:185], v[22:25]
	v_mfma_f32_16x16x32_bf16 v[18:21], v[82:85], v[190:193], v[18:21]
	v_mfma_f32_16x16x32_bf16 v[14:17], v[198:201], v[182:185], v[14:17]
	v_mfma_f32_16x16x32_bf16 v[10:13], v[198:201], v[190:193], v[10:13]
	v_mfma_f32_16x16x32_bf16 v[6:9], v[236:239], v[182:185], v[6:9]
	v_mfma_f32_16x16x32_bf16 v[2:5], v[236:239], v[190:193], v[2:5]
	v_mfma_f32_16x16x32_bf16 v[122:125], v[70:73], v[186:189], v[30:33]
	v_mfma_f32_16x16x32_bf16 v[126:129], v[70:73], v[194:197], v[26:29]
	v_mfma_f32_16x16x32_bf16 v[106:109], v[86:89], v[186:189], v[22:25]
	v_mfma_f32_16x16x32_bf16 v[110:113], v[86:89], v[194:197], v[18:21]
	v_mfma_f32_16x16x32_bf16 v[90:93], v[202:205], v[186:189], v[14:17]
	v_mfma_f32_16x16x32_bf16 v[94:97], v[202:205], v[194:197], v[10:13]
	v_mfma_f32_16x16x32_bf16 v[74:77], v[240:243], v[186:189], v[6:9]
	v_mfma_f32_16x16x32_bf16 v[78:81], v[240:243], v[194:197], v[2:5]
	s_setprio 0
	s_barrier
	s_nop 0
	ds_read_b128 v[2:5], v137 offset:49152
	ds_read_b128 v[6:9], v137 offset:50176
	ds_read_b128 v[244:247], v137 offset:51200
	ds_read_b128 v[248:251], v137 offset:52224
	s_waitcnt vmcnt(0)
	s_barrier
	s_waitcnt lgkmcnt(0)
	s_setprio 3
	s_waitcnt lgkmcnt(0)
	v_mfma_f32_16x16x32_bf16 v[10:13], v[66:69], v[2:5], v[62:65]
	v_mfma_f32_16x16x32_bf16 v[114:117], v[70:73], v[6:9], v[10:13]
	v_mfma_f32_16x16x32_bf16 v[10:13], v[66:69], v[244:247], v[58:61]
	v_mfma_f32_16x16x32_bf16 v[118:121], v[70:73], v[248:251], v[10:13]
	v_mfma_f32_16x16x32_bf16 v[10:13], v[82:85], v[2:5], v[54:57]
	v_mfma_f32_16x16x32_bf16 v[98:101], v[86:89], v[6:9], v[10:13]
	v_mfma_f32_16x16x32_bf16 v[10:13], v[82:85], v[244:247], v[50:53]
	v_mfma_f32_16x16x32_bf16 v[102:105], v[86:89], v[248:251], v[10:13]
	v_mfma_f32_16x16x32_bf16 v[10:13], v[198:201], v[2:5], v[46:49]
	v_mfma_f32_16x16x32_bf16 v[82:85], v[202:205], v[6:9], v[10:13]
	v_mfma_f32_16x16x32_bf16 v[10:13], v[198:201], v[244:247], v[42:45]
	v_mfma_f32_16x16x32_bf16 v[86:89], v[202:205], v[248:251], v[10:13]
	v_mfma_f32_16x16x32_bf16 v[10:13], v[236:239], v[2:5], v[38:41]
	v_mfma_f32_16x16x32_bf16 v[66:69], v[240:243], v[6:9], v[10:13]
	v_mfma_f32_16x16x32_bf16 v[10:13], v[236:239], v[244:247], v[34:37]
	v_mfma_f32_16x16x32_bf16 v[70:73], v[240:243], v[248:251], v[10:13]
	s_setprio 0
	s_barrier
	ds_read_b128 v[18:21], v136 offset:49152
	ds_read_b128 v[22:25], v136 offset:50176
	ds_read_b128 v[38:41], v136 offset:51200
	ds_read_b128 v[198:201], v136 offset:52224
	ds_read_b128 v[202:205], v136 offset:53248
	ds_read_b128 v[236:239], v136 offset:54272
	ds_read_b128 v[240:243], v136 offset:55296
	ds_read_b128 v[138:141], v136 offset:56320
	s_barrier
	s_waitcnt lgkmcnt(0)
	s_setprio 3
	s_waitcnt lgkmcnt(0)
	v_mfma_f32_16x16x32_bf16 v[10:13], v[18:21], v[182:185], v[212:215]
	v_mfma_f32_16x16x32_bf16 v[58:61], v[22:25], v[186:189], v[10:13]
	v_mfma_f32_16x16x32_bf16 v[10:13], v[18:21], v[190:193], v[216:219]
	v_mfma_f32_16x16x32_bf16 v[62:65], v[22:25], v[194:197], v[10:13]
	v_mfma_f32_16x16x32_bf16 v[10:13], v[38:41], v[182:185], v[220:223]
	v_mfma_f32_16x16x32_bf16 v[42:45], v[198:201], v[186:189], v[10:13]
	v_mfma_f32_16x16x32_bf16 v[10:13], v[38:41], v[190:193], v[224:227]
	v_mfma_f32_16x16x32_bf16 v[46:49], v[198:201], v[194:197], v[10:13]
	v_mfma_f32_16x16x32_bf16 v[10:13], v[202:205], v[182:185], v[228:231]
	v_mfma_f32_16x16x32_bf16 v[26:29], v[236:239], v[186:189], v[10:13]
	v_mfma_f32_16x16x32_bf16 v[10:13], v[202:205], v[190:193], v[232:235]
	v_mfma_f32_16x16x32_bf16 v[30:33], v[236:239], v[194:197], v[10:13]
	v_mfma_f32_16x16x32_bf16 v[10:13], v[240:243], v[182:185], v[142:145]
	v_mfma_f32_16x16x32_bf16 v[14:17], v[240:243], v[190:193], v[146:149]
	v_mfma_f32_16x16x32_bf16 v[10:13], v[138:141], v[186:189], v[10:13]
	v_mfma_f32_16x16x32_bf16 v[14:17], v[138:141], v[194:197], v[14:17]
	s_setprio 0
	s_setprio 3
	v_mfma_f32_16x16x32_bf16 v[34:37], v[18:21], v[2:5], v[150:153]
	v_mfma_f32_16x16x32_bf16 v[18:21], v[18:21], v[244:247], v[154:157]
	v_mfma_f32_16x16x32_bf16 v[54:57], v[22:25], v[248:251], v[18:21]
	v_mfma_f32_16x16x32_bf16 v[18:21], v[38:41], v[2:5], v[158:161]
	v_mfma_f32_16x16x32_bf16 v[50:53], v[22:25], v[6:9], v[34:37]
	v_mfma_f32_16x16x32_bf16 v[34:37], v[198:201], v[6:9], v[18:21]
	v_mfma_f32_16x16x32_bf16 v[18:21], v[38:41], v[244:247], v[162:165]
	v_mfma_f32_16x16x32_bf16 v[38:41], v[198:201], v[248:251], v[18:21]
	v_mfma_f32_16x16x32_bf16 v[18:21], v[202:205], v[2:5], v[166:169]
	v_mfma_f32_16x16x32_bf16 v[2:5], v[240:243], v[2:5], v[174:177]
	v_mfma_f32_16x16x32_bf16 v[18:21], v[236:239], v[6:9], v[18:21]
	v_mfma_f32_16x16x32_bf16 v[22:25], v[202:205], v[244:247], v[170:173]
	v_mfma_f32_16x16x32_bf16 v[2:5], v[138:141], v[6:9], v[2:5]
	v_mfma_f32_16x16x32_bf16 v[6:9], v[240:243], v[244:247], v[178:181]
	v_mfma_f32_16x16x32_bf16 v[22:25], v[236:239], v[248:251], v[22:25]
	v_mfma_f32_16x16x32_bf16 v[6:9], v[138:141], v[248:251], v[6:9]
	s_setprio 0
	s_and_b64 vcc, exec, s[10:11]
	s_barrier
	s_cbranch_vccz .LBB0_367
	s_barrier

.LBB0_403:
	ds_read_b128 v[134:137], v217
	ds_read_b128 v[138:141], v217 offset:1024
	ds_read_b128 v[142:145], v217 offset:2048
	ds_read_b128 v[146:149], v217 offset:3072
	s_add_u32 s62, s28, s30
	s_addc_u32 s63, s29, s31
	s_add_u32 s60, s62, 0x80
	s_addc_u32 s61, s63, 0
	s_add_i32 s59, s42, 0xc000
	ds_read_b128 v[150:153], v216
	ds_read_b128 v[154:157], v216 offset:1024
	ds_read_b128 v[158:161], v216 offset:2048
	ds_read_b128 v[162:165], v216 offset:3072
	ds_read_b128 v[166:169], v216 offset:4096
	ds_read_b128 v[170:173], v216 offset:5120
	ds_read_b128 v[174:177], v216 offset:6144
	ds_read_b128 v[178:181], v216 offset:7168
	ds_read_b128 v[182:185], v217 offset:16384
	ds_read_b128 v[186:189], v217 offset:17408
	ds_read_b128 v[190:193], v217 offset:18432
	ds_read_b128 v[194:197], v217 offset:19456
	s_mov_b32 m0, s59
	s_add_i32 s58, s42, 0xe000
	global_load_lds_dwordx4 v132, s[60:61]
	s_mov_b32 m0, s58
	s_nop 0
	global_load_lds_dwordx4 v130, s[60:61]
	s_waitcnt vmcnt(8)
	s_waitcnt lgkmcnt(0)
	s_barrier
	s_setprio 3
	v_mfma_f32_16x16x32_bf16 v[2:5], v[150:153], v[134:137], v[2:5]
	v_mfma_f32_16x16x32_bf16 v[6:9], v[150:153], v[142:145], v[6:9]
	v_mfma_f32_16x16x32_bf16 v[10:13], v[158:161], v[134:137], v[10:13]
	v_mfma_f32_16x16x32_bf16 v[22:25], v[158:161], v[142:145], v[22:25]
	v_mfma_f32_16x16x32_bf16 v[34:37], v[166:169], v[134:137], v[34:37]
	v_mfma_f32_16x16x32_bf16 v[46:49], v[166:169], v[142:145], v[46:49]
	v_mfma_f32_16x16x32_bf16 v[58:61], v[174:177], v[134:137], v[58:61]
	v_mfma_f32_16x16x32_bf16 v[70:73], v[174:177], v[142:145], v[70:73]
	v_mfma_f32_16x16x32_bf16 v[2:5], v[154:157], v[138:141], v[2:5]
	v_mfma_f32_16x16x32_bf16 v[6:9], v[154:157], v[146:149], v[6:9]
	v_mfma_f32_16x16x32_bf16 v[10:13], v[162:165], v[138:141], v[10:13]
	v_mfma_f32_16x16x32_bf16 v[22:25], v[162:165], v[146:149], v[22:25]
	v_mfma_f32_16x16x32_bf16 v[34:37], v[170:173], v[138:141], v[34:37]
	v_mfma_f32_16x16x32_bf16 v[46:49], v[170:173], v[146:149], v[46:49]
	v_mfma_f32_16x16x32_bf16 v[58:61], v[178:181], v[138:141], v[58:61]
	v_mfma_f32_16x16x32_bf16 v[70:73], v[178:181], v[146:149], v[70:73]
	v_mfma_f32_16x16x32_bf16 v[14:17], v[150:153], v[182:185], v[14:17]
	v_mfma_f32_16x16x32_bf16 v[26:29], v[150:153], v[190:193], v[26:29]
	v_mfma_f32_16x16x32_bf16 v[38:41], v[158:161], v[182:185], v[38:41]
	v_mfma_f32_16x16x32_bf16 v[50:53], v[158:161], v[190:193], v[50:53]
	v_mfma_f32_16x16x32_bf16 v[62:65], v[166:169], v[182:185], v[62:65]
	v_mfma_f32_16x16x32_bf16 v[74:77], v[166:169], v[190:193], v[74:77]
	v_mfma_f32_16x16x32_bf16 v[82:85], v[174:177], v[182:185], v[82:85]
	v_mfma_f32_16x16x32_bf16 v[94:97], v[174:177], v[190:193], v[94:97]
	v_mfma_f32_16x16x32_bf16 v[14:17], v[154:157], v[186:189], v[14:17]
	v_mfma_f32_16x16x32_bf16 v[26:29], v[154:157], v[194:197], v[26:29]
	v_mfma_f32_16x16x32_bf16 v[38:41], v[162:165], v[186:189], v[38:41]
	v_mfma_f32_16x16x32_bf16 v[50:53], v[162:165], v[194:197], v[50:53]
	v_mfma_f32_16x16x32_bf16 v[62:65], v[170:173], v[186:189], v[62:65]
	v_mfma_f32_16x16x32_bf16 v[74:77], v[170:173], v[194:197], v[74:77]
	v_mfma_f32_16x16x32_bf16 v[82:85], v[178:181], v[186:189], v[82:85]
	v_mfma_f32_16x16x32_bf16 v[94:97], v[178:181], v[194:197], v[94:97]
	s_setprio 0
	s_barrier
	ds_read_b128 v[150:153], v216 offset:16384
	ds_read_b128 v[154:157], v216 offset:17408
	ds_read_b128 v[158:161], v216 offset:18432
	ds_read_b128 v[162:165], v216 offset:19456
	ds_read_b128 v[166:169], v216 offset:20480
	ds_read_b128 v[170:173], v216 offset:21504
	ds_read_b128 v[174:177], v216 offset:22528
	ds_read_b128 v[178:181], v216 offset:23552
	s_add_i32 s57, s57, 2
	s_add_u32 s64, s22, s30
	s_addc_u32 s65, s23, s31
	s_add_u32 s60, s64, 0x100
	s_addc_u32 s61, s65, 0
	s_mov_b32 m0, s44
	s_nop 0
	global_load_lds_dwordx4 v132, s[60:61]
	s_mov_b32 m0, s45
	s_nop 0
	global_load_lds_dwordx4 v130, s[60:61]
	s_add_u32 s66, s24, s30
	s_addc_u32 s67, s25, s31
	s_add_u32 s60, s66, 0x100
	s_addc_u32 s61, s67, 0
	s_mov_b32 m0, s42
	s_nop 0
	global_load_lds_dwordx4 v132, s[60:61]
	s_mov_b32 m0, s46
	s_nop 0
	global_load_lds_dwordx4 v130, s[60:61]
	s_add_u32 s68, s26, s30
	s_addc_u32 s69, s27, s31
	s_add_u32 s60, s68, 0x100
	s_addc_u32 s61, s69, 0
	s_mov_b32 m0, s47
	s_nop 0
	global_load_lds_dwordx4 v132, s[60:61]
	s_mov_b32 m0, s48
	s_nop 0
	global_load_lds_dwordx4 v130, s[60:61]
	s_waitcnt vmcnt(8)
	s_waitcnt lgkmcnt(0)
	s_barrier
	s_setprio 3
	v_mfma_f32_16x16x32_bf16 v[18:21], v[150:153], v[134:137], v[18:21]
	v_mfma_f32_16x16x32_bf16 v[30:33], v[150:153], v[142:145], v[30:33]
	v_mfma_f32_16x16x32_bf16 v[42:45], v[158:161], v[134:137], v[42:45]
	v_mfma_f32_16x16x32_bf16 v[54:57], v[158:161], v[142:145], v[54:57]
	v_mfma_f32_16x16x32_bf16 v[66:69], v[166:169], v[134:137], v[66:69]
	v_mfma_f32_16x16x32_bf16 v[78:81], v[166:169], v[142:145], v[78:81]
	v_mfma_f32_16x16x32_bf16 v[86:89], v[174:177], v[134:137], v[86:89]
	v_mfma_f32_16x16x32_bf16 v[98:101], v[174:177], v[142:145], v[98:101]
	v_mfma_f32_16x16x32_bf16 v[18:21], v[154:157], v[138:141], v[18:21]
	v_mfma_f32_16x16x32_bf16 v[30:33], v[154:157], v[146:149], v[30:33]
	v_mfma_f32_16x16x32_bf16 v[42:45], v[162:165], v[138:141], v[42:45]
	v_mfma_f32_16x16x32_bf16 v[54:57], v[162:165], v[146:149], v[54:57]
	v_mfma_f32_16x16x32_bf16 v[66:69], v[170:173], v[138:141], v[66:69]
	v_mfma_f32_16x16x32_bf16 v[78:81], v[170:173], v[146:149], v[78:81]
	v_mfma_f32_16x16x32_bf16 v[86:89], v[178:181], v[138:141], v[86:89]
	v_mfma_f32_16x16x32_bf16 v[98:101], v[178:181], v[146:149], v[98:101]
	v_mfma_f32_16x16x32_bf16 v[90:93], v[150:153], v[182:185], v[90:93]
	v_mfma_f32_16x16x32_bf16 v[102:105], v[150:153], v[190:193], v[102:105]
	v_mfma_f32_16x16x32_bf16 v[106:109], v[158:161], v[182:185], v[106:109]
	v_mfma_f32_16x16x32_bf16 v[110:113], v[158:161], v[190:193], v[110:113]
	v_mfma_f32_16x16x32_bf16 v[114:117], v[166:169], v[182:185], v[114:117]
	v_mfma_f32_16x16x32_bf16 v[118:121], v[166:169], v[190:193], v[118:121]
	v_mfma_f32_16x16x32_bf16 v[122:125], v[174:177], v[182:185], v[122:125]
	v_mfma_f32_16x16x32_bf16 v[126:129], v[174:177], v[190:193], v[126:129]
	v_mfma_f32_16x16x32_bf16 v[90:93], v[154:157], v[186:189], v[90:93]
	v_mfma_f32_16x16x32_bf16 v[102:105], v[154:157], v[194:197], v[102:105]
	v_mfma_f32_16x16x32_bf16 v[106:109], v[162:165], v[186:189], v[106:109]
	v_mfma_f32_16x16x32_bf16 v[110:113], v[162:165], v[194:197], v[110:113]
	v_mfma_f32_16x16x32_bf16 v[114:117], v[170:173], v[186:189], v[114:117]
	v_mfma_f32_16x16x32_bf16 v[118:121], v[170:173], v[194:197], v[118:121]
	v_mfma_f32_16x16x32_bf16 v[122:125], v[178:181], v[186:189], v[122:125]
	v_mfma_f32_16x16x32_bf16 v[126:129], v[178:181], v[194:197], v[126:129]
	s_setprio 0
	s_barrier
	ds_read_b128 v[134:137], v217 offset:32768
	ds_read_b128 v[138:141], v217 offset:33792
	ds_read_b128 v[142:145], v217 offset:34816
	ds_read_b128 v[146:149], v217 offset:35840
	s_add_u32 s60, s62, 0x100
	s_addc_u32 s61, s63, 0
	s_mov_b32 m0, s49
	ds_read_b128 v[150:153], v216 offset:32768
	ds_read_b128 v[154:157], v216 offset:33792
	ds_read_b128 v[158:161], v216 offset:34816
	ds_read_b128 v[162:165], v216 offset:35840
	ds_read_b128 v[166:169], v216 offset:36864
	ds_read_b128 v[170:173], v216 offset:37888
	ds_read_b128 v[174:177], v216 offset:38912
	ds_read_b128 v[178:181], v216 offset:39936
	ds_read_b128 v[182:185], v217 offset:49152
	ds_read_b128 v[186:189], v217 offset:50176
	ds_read_b128 v[190:193], v217 offset:51200
	ds_read_b128 v[194:197], v217 offset:52224
	s_nop 0
	global_load_lds_dwordx4 v132, s[60:61]
	s_mov_b32 m0, s50
	s_nop 0
	global_load_lds_dwordx4 v130, s[60:61]
	s_waitcnt vmcnt(8)
	s_waitcnt lgkmcnt(0)
	s_barrier
	s_setprio 3
	v_mfma_f32_16x16x32_bf16 v[2:5], v[150:153], v[134:137], v[2:5]
	v_mfma_f32_16x16x32_bf16 v[6:9], v[150:153], v[142:145], v[6:9]
	v_mfma_f32_16x16x32_bf16 v[10:13], v[158:161], v[134:137], v[10:13]
	v_mfma_f32_16x16x32_bf16 v[22:25], v[158:161], v[142:145], v[22:25]
	v_mfma_f32_16x16x32_bf16 v[34:37], v[166:169], v[134:137], v[34:37]
	v_mfma_f32_16x16x32_bf16 v[46:49], v[166:169], v[142:145], v[46:49]
	v_mfma_f32_16x16x32_bf16 v[58:61], v[174:177], v[134:137], v[58:61]
	v_mfma_f32_16x16x32_bf16 v[70:73], v[174:177], v[142:145], v[70:73]
	v_mfma_f32_16x16x32_bf16 v[2:5], v[154:157], v[138:141], v[2:5]
	v_mfma_f32_16x16x32_bf16 v[6:9], v[154:157], v[146:149], v[6:9]
	v_mfma_f32_16x16x32_bf16 v[10:13], v[162:165], v[138:141], v[10:13]
	v_mfma_f32_16x16x32_bf16 v[22:25], v[162:165], v[146:149], v[22:25]
	v_mfma_f32_16x16x32_bf16 v[34:37], v[170:173], v[138:141], v[34:37]
	v_mfma_f32_16x16x32_bf16 v[46:49], v[170:173], v[146:149], v[46:49]
	v_mfma_f32_16x16x32_bf16 v[58:61], v[178:181], v[138:141], v[58:61]
	v_mfma_f32_16x16x32_bf16 v[70:73], v[178:181], v[146:149], v[70:73]
	v_mfma_f32_16x16x32_bf16 v[14:17], v[150:153], v[182:185], v[14:17]
	v_mfma_f32_16x16x32_bf16 v[26:29], v[150:153], v[190:193], v[26:29]
	v_mfma_f32_16x16x32_bf16 v[38:41], v[158:161], v[182:185], v[38:41]
	v_mfma_f32_16x16x32_bf16 v[50:53], v[158:161], v[190:193], v[50:53]
	v_mfma_f32_16x16x32_bf16 v[62:65], v[166:169], v[182:185], v[62:65]
	v_mfma_f32_16x16x32_bf16 v[74:77], v[166:169], v[190:193], v[74:77]
	v_mfma_f32_16x16x32_bf16 v[82:85], v[174:177], v[182:185], v[82:85]
	v_mfma_f32_16x16x32_bf16 v[94:97], v[174:177], v[190:193], v[94:97]
	v_mfma_f32_16x16x32_bf16 v[14:17], v[154:157], v[186:189], v[14:17]
	v_mfma_f32_16x16x32_bf16 v[26:29], v[154:157], v[194:197], v[26:29]
	v_mfma_f32_16x16x32_bf16 v[38:41], v[162:165], v[186:189], v[38:41]
	v_mfma_f32_16x16x32_bf16 v[50:53], v[162:165], v[194:197], v[50:53]
	v_mfma_f32_16x16x32_bf16 v[62:65], v[170:173], v[186:189], v[62:65]
	v_mfma_f32_16x16x32_bf16 v[74:77], v[170:173], v[194:197], v[74:77]
	v_mfma_f32_16x16x32_bf16 v[82:85], v[178:181], v[186:189], v[82:85]
	v_mfma_f32_16x16x32_bf16 v[94:97], v[178:181], v[194:197], v[94:97]
	s_setprio 0
	s_barrier
	ds_read_b128 v[150:153], v216 offset:49152
	ds_read_b128 v[154:157], v216 offset:50176
	ds_read_b128 v[158:161], v216 offset:51200
	ds_read_b128 v[162:165], v216 offset:52224
	ds_read_b128 v[166:169], v216 offset:53248
	ds_read_b128 v[170:173], v216 offset:54272
	ds_read_b128 v[174:177], v216 offset:55296
	ds_read_b128 v[178:181], v216 offset:56320
	s_add_u32 s60, s64, 0x180
	s_addc_u32 s61, s65, 0
	s_mov_b32 m0, s51
	s_nop 0
	global_load_lds_dwordx4 v132, s[60:61]
	s_mov_b32 m0, s52
	s_nop 0
	global_load_lds_dwordx4 v130, s[60:61]
	s_add_u32 s60, s66, 0x180
	s_addc_u32 s61, s67, 0
	s_mov_b32 m0, s53
	s_nop 0
	global_load_lds_dwordx4 v132, s[60:61]
	s_mov_b32 m0, s54
	s_nop 0
	global_load_lds_dwordx4 v130, s[60:61]
	s_add_u32 s60, s68, 0x180
	s_addc_u32 s61, s69, 0
	s_mov_b32 m0, s55
	s_nop 0
	global_load_lds_dwordx4 v132, s[60:61]
	s_mov_b32 m0, s56
	s_nop 0
	global_load_lds_dwordx4 v130, s[60:61]
	s_waitcnt vmcnt(8)
	s_waitcnt lgkmcnt(0)
	s_barrier
	s_setprio 3
	v_mfma_f32_16x16x32_bf16 v[18:21], v[150:153], v[134:137], v[18:21]
	v_mfma_f32_16x16x32_bf16 v[30:33], v[150:153], v[142:145], v[30:33]
	v_mfma_f32_16x16x32_bf16 v[42:45], v[158:161], v[134:137], v[42:45]
	v_mfma_f32_16x16x32_bf16 v[54:57], v[158:161], v[142:145], v[54:57]
	v_mfma_f32_16x16x32_bf16 v[66:69], v[166:169], v[134:137], v[66:69]
	v_mfma_f32_16x16x32_bf16 v[78:81], v[166:169], v[142:145], v[78:81]
	v_mfma_f32_16x16x32_bf16 v[86:89], v[174:177], v[134:137], v[86:89]
	v_mfma_f32_16x16x32_bf16 v[98:101], v[174:177], v[142:145], v[98:101]
	v_mfma_f32_16x16x32_bf16 v[18:21], v[154:157], v[138:141], v[18:21]
	v_mfma_f32_16x16x32_bf16 v[30:33], v[154:157], v[146:149], v[30:33]
	v_mfma_f32_16x16x32_bf16 v[42:45], v[162:165], v[138:141], v[42:45]
	v_mfma_f32_16x16x32_bf16 v[54:57], v[162:165], v[146:149], v[54:57]
	v_mfma_f32_16x16x32_bf16 v[66:69], v[170:173], v[138:141], v[66:69]
	v_mfma_f32_16x16x32_bf16 v[78:81], v[170:173], v[146:149], v[78:81]
	v_mfma_f32_16x16x32_bf16 v[86:89], v[178:181], v[138:141], v[86:89]
	v_mfma_f32_16x16x32_bf16 v[98:101], v[178:181], v[146:149], v[98:101]
	v_mfma_f32_16x16x32_bf16 v[90:93], v[150:153], v[182:185], v[90:93]
	v_mfma_f32_16x16x32_bf16 v[102:105], v[150:153], v[190:193], v[102:105]
	v_mfma_f32_16x16x32_bf16 v[106:109], v[158:161], v[182:185], v[106:109]
	v_mfma_f32_16x16x32_bf16 v[110:113], v[158:161], v[190:193], v[110:113]
	v_mfma_f32_16x16x32_bf16 v[114:117], v[166:169], v[182:185], v[114:117]
	v_mfma_f32_16x16x32_bf16 v[118:121], v[166:169], v[190:193], v[118:121]
	v_mfma_f32_16x16x32_bf16 v[122:125], v[174:177], v[182:185], v[122:125]
	v_mfma_f32_16x16x32_bf16 v[126:129], v[174:177], v[190:193], v[126:129]
	v_mfma_f32_16x16x32_bf16 v[90:93], v[154:157], v[186:189], v[90:93]
	v_mfma_f32_16x16x32_bf16 v[102:105], v[154:157], v[194:197], v[102:105]
	v_mfma_f32_16x16x32_bf16 v[106:109], v[162:165], v[186:189], v[106:109]
	v_mfma_f32_16x16x32_bf16 v[110:113], v[162:165], v[194:197], v[110:113]
	v_mfma_f32_16x16x32_bf16 v[114:117], v[170:173], v[186:189], v[114:117]
	v_mfma_f32_16x16x32_bf16 v[118:121], v[170:173], v[194:197], v[118:121]
	v_mfma_f32_16x16x32_bf16 v[122:125], v[178:181], v[186:189], v[122:125]
	v_mfma_f32_16x16x32_bf16 v[126:129], v[178:181], v[194:197], v[126:129]
	s_setprio 0
	s_add_u32 s30, s30, 0x100
	s_addc_u32 s31, s31, 0
	s_cmp_ge_u32 s57, s36
	s_barrier
	s_cbranch_scc0 .LBB0_403
	s_add_u32 s22, s28, s14
	s_addc_u32 s23, s29, s15
	s_mov_b32 m0, s59
	ds_read_b128 v[134:137], v217
	ds_read_b128 v[138:141], v217 offset:1024
	ds_read_b128 v[142:145], v217 offset:2048
	ds_read_b128 v[146:149], v217 offset:3072
	ds_read_b128 v[150:153], v216
	ds_read_b128 v[154:157], v216 offset:1024
	ds_read_b128 v[158:161], v216 offset:2048
	ds_read_b128 v[162:165], v216 offset:3072
	ds_read_b128 v[166:169], v216 offset:4096
	ds_read_b128 v[170:173], v216 offset:5120
	ds_read_b128 v[174:177], v216 offset:6144
	ds_read_b128 v[178:181], v216 offset:7168
	s_nop 0
	global_load_lds_dwordx4 v132, s[22:23]
	s_mov_b32 m0, s58
	s_nop 0
	global_load_lds_dwordx4 v130, s[22:23]
	s_waitcnt vmcnt(8)
	s_barrier
	s_waitcnt lgkmcnt(0)
	s_setprio 3
	s_waitcnt lgkmcnt(0)
	v_mfma_f32_16x16x32_bf16 v[2:5], v[150:153], v[134:137], v[2:5]
	v_mfma_f32_16x16x32_bf16 v[6:9], v[150:153], v[142:145], v[6:9]
	v_mfma_f32_16x16x32_bf16 v[10:13], v[158:161], v[134:137], v[10:13]
	v_mfma_f32_16x16x32_bf16 v[22:25], v[158:161], v[142:145], v[22:25]
	v_mfma_f32_16x16x32_bf16 v[34:37], v[166:169], v[134:137], v[34:37]
	v_mfma_f32_16x16x32_bf16 v[46:49], v[166:169], v[142:145], v[46:49]
	v_mfma_f32_16x16x32_bf16 v[58:61], v[174:177], v[134:137], v[58:61]
	v_mfma_f32_16x16x32_bf16 v[70:73], v[174:177], v[142:145], v[70:73]
	v_mfma_f32_16x16x32_bf16 v[2:5], v[154:157], v[138:141], v[2:5]
	v_mfma_f32_16x16x32_bf16 v[6:9], v[154:157], v[146:149], v[6:9]
	v_mfma_f32_16x16x32_bf16 v[10:13], v[162:165], v[138:141], v[10:13]
	v_mfma_f32_16x16x32_bf16 v[22:25], v[162:165], v[146:149], v[22:25]
	v_mfma_f32_16x16x32_bf16 v[34:37], v[170:173], v[138:141], v[34:37]
	v_mfma_f32_16x16x32_bf16 v[46:49], v[170:173], v[146:149], v[46:49]
	v_mfma_f32_16x16x32_bf16 v[58:61], v[178:181], v[138:141], v[58:61]
	v_mfma_f32_16x16x32_bf16 v[70:73], v[178:181], v[146:149], v[70:73]
	s_setprio 0
	s_barrier
	ds_read_b128 v[182:185], v217 offset:16384
	ds_read_b128 v[186:189], v217 offset:17408
	ds_read_b128 v[190:193], v217 offset:18432
	ds_read_b128 v[194:197], v217 offset:19456
	s_barrier
	s_waitcnt lgkmcnt(0)
	s_setprio 3
	s_waitcnt lgkmcnt(0)
	v_mfma_f32_16x16x32_bf16 v[74:77], v[166:169], v[190:193], v[74:77]
	v_mfma_f32_16x16x32_bf16 v[14:17], v[150:153], v[182:185], v[14:17]
	v_mfma_f32_16x16x32_bf16 v[26:29], v[150:153], v[190:193], v[26:29]
	v_mfma_f32_16x16x32_bf16 v[38:41], v[158:161], v[182:185], v[38:41]
	v_mfma_f32_16x16x32_bf16 v[50:53], v[158:161], v[190:193], v[50:53]
	v_mfma_f32_16x16x32_bf16 v[62:65], v[166:169], v[182:185], v[62:65]
	v_mfma_f32_16x16x32_bf16 v[150:153], v[170:173], v[194:197], v[74:77]
	v_mfma_f32_16x16x32_bf16 v[74:77], v[174:177], v[182:185], v[82:85]
	v_mfma_f32_16x16x32_bf16 v[14:17], v[154:157], v[186:189], v[14:17]
	v_mfma_f32_16x16x32_bf16 v[26:29], v[154:157], v[194:197], v[26:29]
	v_mfma_f32_16x16x32_bf16 v[38:41], v[162:165], v[186:189], v[38:41]
	v_mfma_f32_16x16x32_bf16 v[50:53], v[162:165], v[194:197], v[50:53]
	v_mfma_f32_16x16x32_bf16 v[62:65], v[170:173], v[186:189], v[62:65]
	v_mfma_f32_16x16x32_bf16 v[154:157], v[178:181], v[186:189], v[74:77]
	v_mfma_f32_16x16x32_bf16 v[74:77], v[174:177], v[190:193], v[94:97]
	v_mfma_f32_16x16x32_bf16 v[158:161], v[178:181], v[194:197], v[74:77]
	s_setprio 0
	s_barrier
	s_nop 4
	ds_read_b128 v[74:77], v216 offset:16384
	ds_read_b128 v[82:85], v216 offset:17408
	ds_read_b128 v[94:97], v216 offset:18432
	ds_read_b128 v[162:165], v216 offset:19456
	ds_read_b128 v[166:169], v216 offset:20480
	ds_read_b128 v[170:173], v216 offset:21504
	ds_read_b128 v[174:177], v216 offset:22528
	ds_read_b128 v[178:181], v216 offset:23552
	s_waitcnt vmcnt(4)
	s_barrier
	s_waitcnt lgkmcnt(0)
	s_setprio 3
	s_waitcnt lgkmcnt(0)
	v_mfma_f32_16x16x32_bf16 v[66:69], v[166:169], v[134:137], v[66:69]
	v_mfma_f32_16x16x32_bf16 v[198:201], v[170:173], v[138:141], v[66:69]
	v_mfma_f32_16x16x32_bf16 v[66:69], v[166:169], v[142:145], v[78:81]
	v_mfma_f32_16x16x32_bf16 v[18:21], v[74:77], v[134:137], v[18:21]
	v_mfma_f32_16x16x32_bf16 v[30:33], v[74:77], v[142:145], v[30:33]
	v_mfma_f32_16x16x32_bf16 v[42:45], v[94:97], v[134:137], v[42:45]
	v_mfma_f32_16x16x32_bf16 v[54:57], v[94:97], v[142:145], v[54:57]
	v_mfma_f32_16x16x32_bf16 v[202:205], v[170:173], v[146:149], v[66:69]
	v_mfma_f32_16x16x32_bf16 v[66:69], v[174:177], v[134:137], v[86:89]
	v_mfma_f32_16x16x32_bf16 v[18:21], v[82:85], v[138:141], v[18:21]
	v_mfma_f32_16x16x32_bf16 v[30:33], v[82:85], v[146:149], v[30:33]
	v_mfma_f32_16x16x32_bf16 v[42:45], v[162:165], v[138:141], v[42:45]
	v_mfma_f32_16x16x32_bf16 v[54:57], v[162:165], v[146:149], v[54:57]
	v_mfma_f32_16x16x32_bf16 v[134:137], v[178:181], v[138:141], v[66:69]
	v_mfma_f32_16x16x32_bf16 v[66:69], v[174:177], v[142:145], v[98:101]
	v_mfma_f32_16x16x32_bf16 v[138:141], v[178:181], v[146:149], v[66:69]
	s_setprio 0
	s_setprio 3
	v_mfma_f32_16x16x32_bf16 v[66:69], v[74:77], v[182:185], v[90:93]
	v_mfma_f32_16x16x32_bf16 v[142:145], v[82:85], v[186:189], v[66:69]
	v_mfma_f32_16x16x32_bf16 v[66:69], v[74:77], v[190:193], v[102:105]
	v_mfma_f32_16x16x32_bf16 v[146:149], v[82:85], v[194:197], v[66:69]
	v_mfma_f32_16x16x32_bf16 v[66:69], v[94:97], v[182:185], v[106:109]
	v_mfma_f32_16x16x32_bf16 v[212:215], v[162:165], v[186:189], v[66:69]
	v_mfma_f32_16x16x32_bf16 v[66:69], v[94:97], v[190:193], v[110:113]
	v_mfma_f32_16x16x32_bf16 v[162:165], v[162:165], v[194:197], v[66:69]
	v_mfma_f32_16x16x32_bf16 v[66:69], v[166:169], v[182:185], v[114:117]
	v_mfma_f32_16x16x32_bf16 v[220:223], v[170:173], v[186:189], v[66:69]
	v_mfma_f32_16x16x32_bf16 v[66:69], v[166:169], v[190:193], v[118:121]
	v_mfma_f32_16x16x32_bf16 v[166:169], v[170:173], v[194:197], v[66:69]
	v_mfma_f32_16x16x32_bf16 v[66:69], v[174:177], v[182:185], v[122:125]
	v_mfma_f32_16x16x32_bf16 v[170:173], v[178:181], v[186:189], v[66:69]
	v_mfma_f32_16x16x32_bf16 v[66:69], v[174:177], v[190:193], v[126:129]
	v_mfma_f32_16x16x32_bf16 v[174:177], v[178:181], v[194:197], v[66:69]
	s_setprio 0
	s_barrier
	ds_read_b128 v[178:181], v217 offset:32768
	ds_read_b128 v[182:185], v217 offset:33792
	ds_read_b128 v[186:189], v217 offset:34816
	ds_read_b128 v[190:193], v217 offset:35840
	s_nop 0
	ds_read_b128 v[66:69], v216 offset:32768
	ds_read_b128 v[82:85], v216 offset:33792
	ds_read_b128 v[86:89], v216 offset:34816
	ds_read_b128 v[102:105], v216 offset:35840
	ds_read_b128 v[194:197], v216 offset:36864
	ds_read_b128 v[224:227], v216 offset:37888
	ds_read_b128 v[228:231], v216 offset:38912
	ds_read_b128 v[232:235], v216 offset:39936
	s_waitcnt vmcnt(2)
	s_barrier
	s_waitcnt lgkmcnt(0)
	s_setprio 3
	s_waitcnt lgkmcnt(0)
	v_mfma_f32_16x16x32_bf16 v[2:5], v[66:69], v[178:181], v[2:5]
	v_mfma_f32_16x16x32_bf16 v[122:125], v[82:85], v[182:185], v[2:5]
	v_mfma_f32_16x16x32_bf16 v[2:5], v[66:69], v[186:189], v[6:9]
	v_mfma_f32_16x16x32_bf16 v[126:129], v[82:85], v[190:193], v[2:5]
	v_mfma_f32_16x16x32_bf16 v[2:5], v[86:89], v[178:181], v[10:13]
	v_mfma_f32_16x16x32_bf16 v[106:109], v[102:105], v[182:185], v[2:5]
	v_mfma_f32_16x16x32_bf16 v[2:5], v[86:89], v[186:189], v[22:25]
	v_mfma_f32_16x16x32_bf16 v[110:113], v[102:105], v[190:193], v[2:5]
	v_mfma_f32_16x16x32_bf16 v[2:5], v[194:197], v[178:181], v[34:37]
	v_mfma_f32_16x16x32_bf16 v[90:93], v[224:227], v[182:185], v[2:5]
	v_mfma_f32_16x16x32_bf16 v[2:5], v[194:197], v[186:189], v[46:49]
	v_mfma_f32_16x16x32_bf16 v[94:97], v[224:227], v[190:193], v[2:5]
	v_mfma_f32_16x16x32_bf16 v[2:5], v[228:231], v[178:181], v[58:61]
	v_mfma_f32_16x16x32_bf16 v[74:77], v[232:235], v[182:185], v[2:5]
	v_mfma_f32_16x16x32_bf16 v[2:5], v[228:231], v[186:189], v[70:73]
	v_mfma_f32_16x16x32_bf16 v[78:81], v[232:235], v[190:193], v[2:5]
	s_setprio 0
	s_barrier
	s_nop 4
	ds_read_b128 v[2:5], v217 offset:49152
	ds_read_b128 v[6:9], v217 offset:50176
	ds_read_b128 v[236:239], v217 offset:51200
	ds_read_b128 v[240:243], v217 offset:52224
	s_waitcnt vmcnt(0)
	s_barrier
	s_waitcnt lgkmcnt(0)
	s_setprio 3
	s_waitcnt lgkmcnt(0)
	v_mfma_f32_16x16x32_bf16 v[10:13], v[66:69], v[2:5], v[14:17]
	v_mfma_f32_16x16x32_bf16 v[114:117], v[82:85], v[6:9], v[10:13]
	v_mfma_f32_16x16x32_bf16 v[10:13], v[66:69], v[236:239], v[26:29]
	v_mfma_f32_16x16x32_bf16 v[118:121], v[82:85], v[240:243], v[10:13]
	v_mfma_f32_16x16x32_bf16 v[10:13], v[86:89], v[2:5], v[38:41]
	v_mfma_f32_16x16x32_bf16 v[98:101], v[102:105], v[6:9], v[10:13]
	v_mfma_f32_16x16x32_bf16 v[10:13], v[86:89], v[236:239], v[50:53]
	v_mfma_f32_16x16x32_bf16 v[102:105], v[102:105], v[240:243], v[10:13]
	v_mfma_f32_16x16x32_bf16 v[10:13], v[194:197], v[2:5], v[62:65]
	v_mfma_f32_16x16x32_bf16 v[82:85], v[224:227], v[6:9], v[10:13]
	v_mfma_f32_16x16x32_bf16 v[10:13], v[194:197], v[236:239], v[150:153]
	v_mfma_f32_16x16x32_bf16 v[86:89], v[224:227], v[240:243], v[10:13]
	v_mfma_f32_16x16x32_bf16 v[10:13], v[228:231], v[2:5], v[154:157]
	v_mfma_f32_16x16x32_bf16 v[66:69], v[232:235], v[6:9], v[10:13]
	v_mfma_f32_16x16x32_bf16 v[10:13], v[228:231], v[236:239], v[158:161]
	v_mfma_f32_16x16x32_bf16 v[70:73], v[232:235], v[240:243], v[10:13]
	s_setprio 0
	s_barrier
	ds_read_b128 v[22:25], v216 offset:49152
	ds_read_b128 v[34:37], v216 offset:50176
	ds_read_b128 v[38:41], v216 offset:51200
	ds_read_b128 v[150:153], v216 offset:52224
	ds_read_b128 v[154:157], v216 offset:53248
	ds_read_b128 v[158:161], v216 offset:54272
	ds_read_b128 v[194:197], v216 offset:55296
	ds_read_b128 v[224:227], v216 offset:56320
	s_barrier
	s_waitcnt lgkmcnt(0)
	s_setprio 3
	s_waitcnt lgkmcnt(0)
	v_mfma_f32_16x16x32_bf16 v[10:13], v[22:25], v[178:181], v[18:21]
	v_mfma_f32_16x16x32_bf16 v[58:61], v[34:37], v[182:185], v[10:13]
	v_mfma_f32_16x16x32_bf16 v[10:13], v[22:25], v[186:189], v[30:33]
	v_mfma_f32_16x16x32_bf16 v[62:65], v[34:37], v[190:193], v[10:13]
	v_mfma_f32_16x16x32_bf16 v[10:13], v[38:41], v[178:181], v[42:45]
	v_mfma_f32_16x16x32_bf16 v[42:45], v[150:153], v[182:185], v[10:13]
	v_mfma_f32_16x16x32_bf16 v[10:13], v[38:41], v[186:189], v[54:57]
	v_mfma_f32_16x16x32_bf16 v[46:49], v[150:153], v[190:193], v[10:13]
	v_mfma_f32_16x16x32_bf16 v[10:13], v[154:157], v[178:181], v[198:201]
	v_mfma_f32_16x16x32_bf16 v[26:29], v[158:161], v[182:185], v[10:13]
	v_mfma_f32_16x16x32_bf16 v[10:13], v[154:157], v[186:189], v[202:205]
	v_mfma_f32_16x16x32_bf16 v[30:33], v[158:161], v[190:193], v[10:13]
	v_mfma_f32_16x16x32_bf16 v[10:13], v[194:197], v[178:181], v[134:137]
	v_mfma_f32_16x16x32_bf16 v[14:17], v[194:197], v[186:189], v[138:141]
	v_mfma_f32_16x16x32_bf16 v[10:13], v[224:227], v[182:185], v[10:13]
	v_mfma_f32_16x16x32_bf16 v[14:17], v[224:227], v[190:193], v[14:17]
	s_setprio 0
	s_setprio 3
	v_mfma_f32_16x16x32_bf16 v[18:21], v[22:25], v[2:5], v[142:145]
	v_mfma_f32_16x16x32_bf16 v[50:53], v[34:37], v[6:9], v[18:21]
	v_mfma_f32_16x16x32_bf16 v[18:21], v[22:25], v[236:239], v[146:149]
	v_mfma_f32_16x16x32_bf16 v[54:57], v[34:37], v[240:243], v[18:21]
	v_mfma_f32_16x16x32_bf16 v[18:21], v[38:41], v[2:5], v[212:215]
	v_mfma_f32_16x16x32_bf16 v[34:37], v[150:153], v[6:9], v[18:21]
	v_mfma_f32_16x16x32_bf16 v[18:21], v[38:41], v[236:239], v[162:165]
	v_mfma_f32_16x16x32_bf16 v[38:41], v[150:153], v[240:243], v[18:21]
	v_mfma_f32_16x16x32_bf16 v[18:21], v[154:157], v[2:5], v[220:223]
	v_mfma_f32_16x16x32_bf16 v[2:5], v[194:197], v[2:5], v[170:173]
	v_mfma_f32_16x16x32_bf16 v[18:21], v[158:161], v[6:9], v[18:21]
	v_mfma_f32_16x16x32_bf16 v[22:25], v[154:157], v[236:239], v[166:169]
	v_mfma_f32_16x16x32_bf16 v[2:5], v[224:227], v[6:9], v[2:5]
	v_mfma_f32_16x16x32_bf16 v[6:9], v[194:197], v[236:239], v[174:177]
	v_mfma_f32_16x16x32_bf16 v[22:25], v[158:161], v[240:243], v[22:25]
	v_mfma_f32_16x16x32_bf16 v[6:9], v[224:227], v[240:243], v[6:9]
	s_setprio 0
	s_and_b64 vcc, exec, s[16:17]
	s_barrier
	s_cbranch_vccz .LBB0_406
	s_barrier

.LBB0_468:
	ds_read_b128 v[138:141], v137
	ds_read_b128 v[142:145], v137 offset:1024
	ds_read_b128 v[146:149], v137 offset:2048
	ds_read_b128 v[150:153], v137 offset:3072
	s_add_u32 s57, s18, s16
	s_addc_u32 s60, s19, s17
	s_add_u32 s58, s57, 0x180
	s_addc_u32 s59, s60, 0
	s_mov_b32 m0, s40
	ds_read_b128 v[154:157], v136
	ds_read_b128 v[158:161], v136 offset:1024
	ds_read_b128 v[162:165], v136 offset:2048
	ds_read_b128 v[166:169], v136 offset:3072
	ds_read_b128 v[170:173], v136 offset:4096
	ds_read_b128 v[174:177], v136 offset:5120
	ds_read_b128 v[178:181], v136 offset:6144
	ds_read_b128 v[182:185], v136 offset:7168
	ds_read_b128 v[186:189], v137 offset:16384
	ds_read_b128 v[190:193], v137 offset:17408
	ds_read_b128 v[194:197], v137 offset:18432
	ds_read_b128 v[198:201], v137 offset:19456
	s_nop 0
	global_load_lds_dwordx4 v130, s[58:59]
	s_mov_b32 m0, s41
	s_nop 0
	global_load_lds_dwordx4 v132, s[58:59]
	s_waitcnt vmcnt(8)
	s_waitcnt lgkmcnt(0)
	s_barrier
	s_setprio 3
	v_mfma_f32_16x16x32_bf16 v[30:33], v[154:157], v[138:141], v[30:33]
	v_mfma_f32_16x16x32_bf16 v[26:29], v[154:157], v[146:149], v[26:29]
	v_mfma_f32_16x16x32_bf16 v[22:25], v[162:165], v[138:141], v[22:25]
	v_mfma_f32_16x16x32_bf16 v[18:21], v[162:165], v[146:149], v[18:21]
	v_mfma_f32_16x16x32_bf16 v[14:17], v[170:173], v[138:141], v[14:17]
	v_mfma_f32_16x16x32_bf16 v[10:13], v[170:173], v[146:149], v[10:13]
	v_mfma_f32_16x16x32_bf16 v[6:9], v[178:181], v[138:141], v[6:9]
	v_mfma_f32_16x16x32_bf16 v[2:5], v[178:181], v[146:149], v[2:5]
	v_mfma_f32_16x16x32_bf16 v[30:33], v[158:161], v[142:145], v[30:33]
	v_mfma_f32_16x16x32_bf16 v[26:29], v[158:161], v[150:153], v[26:29]
	v_mfma_f32_16x16x32_bf16 v[22:25], v[166:169], v[142:145], v[22:25]
	v_mfma_f32_16x16x32_bf16 v[18:21], v[166:169], v[150:153], v[18:21]
	v_mfma_f32_16x16x32_bf16 v[14:17], v[174:177], v[142:145], v[14:17]
	v_mfma_f32_16x16x32_bf16 v[10:13], v[174:177], v[150:153], v[10:13]
	v_mfma_f32_16x16x32_bf16 v[6:9], v[182:185], v[142:145], v[6:9]
	v_mfma_f32_16x16x32_bf16 v[2:5], v[182:185], v[150:153], v[2:5]
	v_mfma_f32_16x16x32_bf16 v[62:65], v[154:157], v[186:189], v[62:65]
	v_mfma_f32_16x16x32_bf16 v[58:61], v[154:157], v[194:197], v[58:61]
	v_mfma_f32_16x16x32_bf16 v[54:57], v[162:165], v[186:189], v[54:57]
	v_mfma_f32_16x16x32_bf16 v[50:53], v[162:165], v[194:197], v[50:53]
	v_mfma_f32_16x16x32_bf16 v[46:49], v[170:173], v[186:189], v[46:49]
	v_mfma_f32_16x16x32_bf16 v[42:45], v[170:173], v[194:197], v[42:45]
	v_mfma_f32_16x16x32_bf16 v[38:41], v[178:181], v[186:189], v[38:41]
	v_mfma_f32_16x16x32_bf16 v[34:37], v[178:181], v[194:197], v[34:37]
	v_mfma_f32_16x16x32_bf16 v[62:65], v[158:161], v[190:193], v[62:65]
	v_mfma_f32_16x16x32_bf16 v[58:61], v[158:161], v[198:201], v[58:61]
	v_mfma_f32_16x16x32_bf16 v[54:57], v[166:169], v[190:193], v[54:57]
	v_mfma_f32_16x16x32_bf16 v[50:53], v[166:169], v[198:201], v[50:53]
	v_mfma_f32_16x16x32_bf16 v[46:49], v[174:177], v[190:193], v[46:49]
	v_mfma_f32_16x16x32_bf16 v[42:45], v[174:177], v[198:201], v[42:45]
	v_mfma_f32_16x16x32_bf16 v[38:41], v[182:185], v[190:193], v[38:41]
	v_mfma_f32_16x16x32_bf16 v[34:37], v[182:185], v[198:201], v[34:37]
	s_setprio 0
	s_barrier
	ds_read_b128 v[154:157], v136 offset:16384
	ds_read_b128 v[158:161], v136 offset:17408
	ds_read_b128 v[162:165], v136 offset:18432
	ds_read_b128 v[166:169], v136 offset:19456
	ds_read_b128 v[170:173], v136 offset:20480
	ds_read_b128 v[174:177], v136 offset:21504
	ds_read_b128 v[178:181], v136 offset:22528
	ds_read_b128 v[182:185], v136 offset:23552
	s_add_u32 s61, s51, s16
	s_addc_u32 s62, s52, s17
	s_add_u32 s58, s61, 0x200
	s_addc_u32 s59, s62, 0
	s_mov_b32 m0, s26
	s_nop 0
	global_load_lds_dwordx4 v130, s[58:59]
	s_mov_b32 m0, s27
	s_nop 0
	global_load_lds_dwordx4 v132, s[58:59]
	s_add_u32 s63, s13, s16
	s_addc_u32 s64, s53, s17
	s_add_u32 s58, s63, 0x200
	s_addc_u32 s59, s64, 0
	s_mov_b32 m0, s25
	s_nop 0
	global_load_lds_dwordx4 v130, s[58:59]
	s_mov_b32 m0, s28
	s_nop 0
	global_load_lds_dwordx4 v132, s[58:59]
	s_add_u32 s65, s54, s16
	s_addc_u32 s66, s55, s17
	s_add_u32 s58, s65, 0x200
	s_addc_u32 s59, s66, 0
	s_mov_b32 m0, s29
	s_nop 0
	global_load_lds_dwordx4 v130, s[58:59]
	s_mov_b32 m0, s30
	s_nop 0
	global_load_lds_dwordx4 v132, s[58:59]
	s_waitcnt vmcnt(8)
	s_waitcnt lgkmcnt(0)
	s_barrier
	s_setprio 3
	v_mfma_f32_16x16x32_bf16 v[94:97], v[154:157], v[138:141], v[94:97]
	v_mfma_f32_16x16x32_bf16 v[90:93], v[154:157], v[146:149], v[90:93]
	v_mfma_f32_16x16x32_bf16 v[86:89], v[162:165], v[138:141], v[86:89]
	v_mfma_f32_16x16x32_bf16 v[82:85], v[162:165], v[146:149], v[82:85]
	v_mfma_f32_16x16x32_bf16 v[78:81], v[170:173], v[138:141], v[78:81]
	v_mfma_f32_16x16x32_bf16 v[74:77], v[170:173], v[146:149], v[74:77]
	v_mfma_f32_16x16x32_bf16 v[70:73], v[178:181], v[138:141], v[70:73]
	v_mfma_f32_16x16x32_bf16 v[66:69], v[178:181], v[146:149], v[66:69]
	v_mfma_f32_16x16x32_bf16 v[94:97], v[158:161], v[142:145], v[94:97]
	v_mfma_f32_16x16x32_bf16 v[90:93], v[158:161], v[150:153], v[90:93]
	v_mfma_f32_16x16x32_bf16 v[86:89], v[166:169], v[142:145], v[86:89]
	v_mfma_f32_16x16x32_bf16 v[82:85], v[166:169], v[150:153], v[82:85]
	v_mfma_f32_16x16x32_bf16 v[78:81], v[174:177], v[142:145], v[78:81]
	v_mfma_f32_16x16x32_bf16 v[74:77], v[174:177], v[150:153], v[74:77]
	v_mfma_f32_16x16x32_bf16 v[70:73], v[182:185], v[142:145], v[70:73]
	v_mfma_f32_16x16x32_bf16 v[66:69], v[182:185], v[150:153], v[66:69]
	v_mfma_f32_16x16x32_bf16 v[126:129], v[154:157], v[186:189], v[126:129]
	v_mfma_f32_16x16x32_bf16 v[122:125], v[154:157], v[194:197], v[122:125]
	v_mfma_f32_16x16x32_bf16 v[118:121], v[162:165], v[186:189], v[118:121]
	v_mfma_f32_16x16x32_bf16 v[114:117], v[162:165], v[194:197], v[114:117]
	v_mfma_f32_16x16x32_bf16 v[110:113], v[170:173], v[186:189], v[110:113]
	v_mfma_f32_16x16x32_bf16 v[106:109], v[170:173], v[194:197], v[106:109]
	v_mfma_f32_16x16x32_bf16 v[102:105], v[178:181], v[186:189], v[102:105]
	v_mfma_f32_16x16x32_bf16 v[98:101], v[178:181], v[194:197], v[98:101]
	v_mfma_f32_16x16x32_bf16 v[126:129], v[158:161], v[190:193], v[126:129]
	v_mfma_f32_16x16x32_bf16 v[122:125], v[158:161], v[198:201], v[122:125]
	v_mfma_f32_16x16x32_bf16 v[118:121], v[166:169], v[190:193], v[118:121]
	v_mfma_f32_16x16x32_bf16 v[114:117], v[166:169], v[198:201], v[114:117]
	v_mfma_f32_16x16x32_bf16 v[110:113], v[174:177], v[190:193], v[110:113]
	v_mfma_f32_16x16x32_bf16 v[106:109], v[174:177], v[198:201], v[106:109]
	v_mfma_f32_16x16x32_bf16 v[102:105], v[182:185], v[190:193], v[102:105]
	v_mfma_f32_16x16x32_bf16 v[98:101], v[182:185], v[198:201], v[98:101]
	s_setprio 0
	s_barrier
	ds_read_b128 v[138:141], v137 offset:32768
	ds_read_b128 v[142:145], v137 offset:33792
	ds_read_b128 v[146:149], v137 offset:34816
	ds_read_b128 v[150:153], v137 offset:35840
	s_add_u32 s58, s57, 0x200
	s_addc_u32 s59, s60, 0
	s_mov_b32 m0, s31
	ds_read_b128 v[154:157], v136 offset:32768
	ds_read_b128 v[158:161], v136 offset:33792
	ds_read_b128 v[162:165], v136 offset:34816
	ds_read_b128 v[166:169], v136 offset:35840
	ds_read_b128 v[170:173], v136 offset:36864
	ds_read_b128 v[174:177], v136 offset:37888
	ds_read_b128 v[178:181], v136 offset:38912
	ds_read_b128 v[182:185], v136 offset:39936
	ds_read_b128 v[186:189], v137 offset:49152
	ds_read_b128 v[190:193], v137 offset:50176
	ds_read_b128 v[194:197], v137 offset:51200
	ds_read_b128 v[198:201], v137 offset:52224
	s_nop 0
	global_load_lds_dwordx4 v130, s[58:59]
	s_mov_b32 m0, s33
	s_nop 0
	global_load_lds_dwordx4 v132, s[58:59]
	s_waitcnt vmcnt(8)
	s_waitcnt lgkmcnt(0)
	s_barrier
	s_setprio 3
	v_mfma_f32_16x16x32_bf16 v[30:33], v[154:157], v[138:141], v[30:33]
	v_mfma_f32_16x16x32_bf16 v[26:29], v[154:157], v[146:149], v[26:29]
	v_mfma_f32_16x16x32_bf16 v[22:25], v[162:165], v[138:141], v[22:25]
	v_mfma_f32_16x16x32_bf16 v[18:21], v[162:165], v[146:149], v[18:21]
	v_mfma_f32_16x16x32_bf16 v[14:17], v[170:173], v[138:141], v[14:17]
	v_mfma_f32_16x16x32_bf16 v[10:13], v[170:173], v[146:149], v[10:13]
	v_mfma_f32_16x16x32_bf16 v[6:9], v[178:181], v[138:141], v[6:9]
	v_mfma_f32_16x16x32_bf16 v[2:5], v[178:181], v[146:149], v[2:5]
	v_mfma_f32_16x16x32_bf16 v[30:33], v[158:161], v[142:145], v[30:33]
	v_mfma_f32_16x16x32_bf16 v[26:29], v[158:161], v[150:153], v[26:29]
	v_mfma_f32_16x16x32_bf16 v[22:25], v[166:169], v[142:145], v[22:25]
	v_mfma_f32_16x16x32_bf16 v[18:21], v[166:169], v[150:153], v[18:21]
	v_mfma_f32_16x16x32_bf16 v[14:17], v[174:177], v[142:145], v[14:17]
	v_mfma_f32_16x16x32_bf16 v[10:13], v[174:177], v[150:153], v[10:13]
	v_mfma_f32_16x16x32_bf16 v[6:9], v[182:185], v[142:145], v[6:9]
	v_mfma_f32_16x16x32_bf16 v[2:5], v[182:185], v[150:153], v[2:5]
	v_mfma_f32_16x16x32_bf16 v[62:65], v[154:157], v[186:189], v[62:65]
	v_mfma_f32_16x16x32_bf16 v[58:61], v[154:157], v[194:197], v[58:61]
	v_mfma_f32_16x16x32_bf16 v[54:57], v[162:165], v[186:189], v[54:57]
	v_mfma_f32_16x16x32_bf16 v[50:53], v[162:165], v[194:197], v[50:53]
	v_mfma_f32_16x16x32_bf16 v[46:49], v[170:173], v[186:189], v[46:49]
	v_mfma_f32_16x16x32_bf16 v[42:45], v[170:173], v[194:197], v[42:45]
	v_mfma_f32_16x16x32_bf16 v[38:41], v[178:181], v[186:189], v[38:41]
	v_mfma_f32_16x16x32_bf16 v[34:37], v[178:181], v[194:197], v[34:37]
	v_mfma_f32_16x16x32_bf16 v[62:65], v[158:161], v[190:193], v[62:65]
	v_mfma_f32_16x16x32_bf16 v[58:61], v[158:161], v[198:201], v[58:61]
	v_mfma_f32_16x16x32_bf16 v[54:57], v[166:169], v[190:193], v[54:57]
	v_mfma_f32_16x16x32_bf16 v[50:53], v[166:169], v[198:201], v[50:53]
	v_mfma_f32_16x16x32_bf16 v[46:49], v[174:177], v[190:193], v[46:49]
	v_mfma_f32_16x16x32_bf16 v[42:45], v[174:177], v[198:201], v[42:45]
	v_mfma_f32_16x16x32_bf16 v[38:41], v[182:185], v[190:193], v[38:41]
	v_mfma_f32_16x16x32_bf16 v[34:37], v[182:185], v[198:201], v[34:37]
	s_setprio 0
	s_barrier
	ds_read_b128 v[154:157], v136 offset:49152
	ds_read_b128 v[158:161], v136 offset:50176
	ds_read_b128 v[162:165], v136 offset:51200
	ds_read_b128 v[166:169], v136 offset:52224
	ds_read_b128 v[170:173], v136 offset:53248
	ds_read_b128 v[174:177], v136 offset:54272
	ds_read_b128 v[178:181], v136 offset:55296
	ds_read_b128 v[182:185], v136 offset:56320
	s_add_u32 s58, s61, 0x280
	s_addc_u32 s59, s62, 0
	s_mov_b32 m0, s34
	s_nop 0
	global_load_lds_dwordx4 v130, s[58:59]
	s_mov_b32 m0, s35
	s_nop 0
	global_load_lds_dwordx4 v132, s[58:59]
	s_add_u32 s58, s63, 0x280
	s_addc_u32 s59, s64, 0
	s_mov_b32 m0, s36
	s_nop 0
	global_load_lds_dwordx4 v130, s[58:59]
	s_mov_b32 m0, s37
	s_nop 0
	global_load_lds_dwordx4 v132, s[58:59]
	s_add_u32 s58, s65, 0x280
	s_addc_u32 s59, s66, 0
	s_mov_b32 m0, s38
	s_nop 0
	global_load_lds_dwordx4 v130, s[58:59]
	s_mov_b32 m0, s39
	s_nop 0
	global_load_lds_dwordx4 v132, s[58:59]
	s_waitcnt vmcnt(8)
	s_waitcnt lgkmcnt(0)
	s_barrier
	s_setprio 3
	v_mfma_f32_16x16x32_bf16 v[94:97], v[154:157], v[138:141], v[94:97]
	v_mfma_f32_16x16x32_bf16 v[90:93], v[154:157], v[146:149], v[90:93]
	v_mfma_f32_16x16x32_bf16 v[86:89], v[162:165], v[138:141], v[86:89]
	v_mfma_f32_16x16x32_bf16 v[82:85], v[162:165], v[146:149], v[82:85]
	v_mfma_f32_16x16x32_bf16 v[78:81], v[170:173], v[138:141], v[78:81]
	v_mfma_f32_16x16x32_bf16 v[74:77], v[170:173], v[146:149], v[74:77]
	v_mfma_f32_16x16x32_bf16 v[70:73], v[178:181], v[138:141], v[70:73]
	v_mfma_f32_16x16x32_bf16 v[66:69], v[178:181], v[146:149], v[66:69]
	v_mfma_f32_16x16x32_bf16 v[94:97], v[158:161], v[142:145], v[94:97]
	v_mfma_f32_16x16x32_bf16 v[90:93], v[158:161], v[150:153], v[90:93]
	v_mfma_f32_16x16x32_bf16 v[86:89], v[166:169], v[142:145], v[86:89]
	v_mfma_f32_16x16x32_bf16 v[82:85], v[166:169], v[150:153], v[82:85]
	v_mfma_f32_16x16x32_bf16 v[78:81], v[174:177], v[142:145], v[78:81]
	v_mfma_f32_16x16x32_bf16 v[74:77], v[174:177], v[150:153], v[74:77]
	v_mfma_f32_16x16x32_bf16 v[70:73], v[182:185], v[142:145], v[70:73]
	v_mfma_f32_16x16x32_bf16 v[66:69], v[182:185], v[150:153], v[66:69]
	v_mfma_f32_16x16x32_bf16 v[126:129], v[154:157], v[186:189], v[126:129]
	v_mfma_f32_16x16x32_bf16 v[122:125], v[154:157], v[194:197], v[122:125]
	v_mfma_f32_16x16x32_bf16 v[118:121], v[162:165], v[186:189], v[118:121]
	v_mfma_f32_16x16x32_bf16 v[114:117], v[162:165], v[194:197], v[114:117]
	v_mfma_f32_16x16x32_bf16 v[110:113], v[170:173], v[186:189], v[110:113]
	v_mfma_f32_16x16x32_bf16 v[106:109], v[170:173], v[194:197], v[106:109]
	v_mfma_f32_16x16x32_bf16 v[102:105], v[178:181], v[186:189], v[102:105]
	v_mfma_f32_16x16x32_bf16 v[98:101], v[178:181], v[194:197], v[98:101]
	v_mfma_f32_16x16x32_bf16 v[126:129], v[158:161], v[190:193], v[126:129]
	v_mfma_f32_16x16x32_bf16 v[122:125], v[158:161], v[198:201], v[122:125]
	v_mfma_f32_16x16x32_bf16 v[118:121], v[166:169], v[190:193], v[118:121]
	v_mfma_f32_16x16x32_bf16 v[114:117], v[166:169], v[198:201], v[114:117]
	v_mfma_f32_16x16x32_bf16 v[110:113], v[174:177], v[190:193], v[110:113]
	v_mfma_f32_16x16x32_bf16 v[106:109], v[174:177], v[198:201], v[106:109]
	v_mfma_f32_16x16x32_bf16 v[102:105], v[182:185], v[190:193], v[102:105]
	v_mfma_f32_16x16x32_bf16 v[98:101], v[182:185], v[198:201], v[98:101]
	s_setprio 0
	s_add_i32 s56, s56, 2
	s_add_u32 s16, s16, 0x100
	s_addc_u32 s17, s17, 0
	s_cmp_gt_u32 s56, 11
	s_barrier
	s_cbranch_scc0 .LBB0_468
	s_lshl_b64 s[14:15], s[14:15], 1
	s_add_u32 s14, s42, s14
	s_addc_u32 s15, s43, s15
	s_mov_b32 m0, s40
	ds_read_b128 v[142:145], v137
	ds_read_b128 v[146:149], v137 offset:1024
	ds_read_b128 v[150:153], v137 offset:2048
	ds_read_b128 v[154:157], v137 offset:3072
	ds_read_b128 v[158:161], v136
	ds_read_b128 v[162:165], v136 offset:1024
	ds_read_b128 v[166:169], v136 offset:2048
	ds_read_b128 v[170:173], v136 offset:3072
	ds_read_b128 v[174:177], v136 offset:4096
	ds_read_b128 v[178:181], v136 offset:5120
	ds_read_b128 v[182:185], v136 offset:6144
	ds_read_b128 v[186:189], v136 offset:7168
	s_nop 0
	global_load_lds_dwordx4 v130, s[14:15]
	s_mov_b32 m0, s41
	s_nop 0
	global_load_lds_dwordx4 v132, s[14:15]
	s_waitcnt vmcnt(8)
	s_barrier
	s_waitcnt lgkmcnt(0)
	s_setprio 3
	s_waitcnt lgkmcnt(0)
	v_mfma_f32_16x16x32_bf16 v[30:33], v[158:161], v[142:145], v[30:33]
	v_mfma_f32_16x16x32_bf16 v[26:29], v[158:161], v[150:153], v[26:29]
	v_mfma_f32_16x16x32_bf16 v[22:25], v[166:169], v[142:145], v[22:25]
	v_mfma_f32_16x16x32_bf16 v[18:21], v[166:169], v[150:153], v[18:21]
	v_mfma_f32_16x16x32_bf16 v[14:17], v[174:177], v[142:145], v[14:17]
	v_mfma_f32_16x16x32_bf16 v[10:13], v[174:177], v[150:153], v[10:13]
	v_mfma_f32_16x16x32_bf16 v[6:9], v[182:185], v[142:145], v[6:9]
	v_mfma_f32_16x16x32_bf16 v[2:5], v[182:185], v[150:153], v[2:5]
	v_mfma_f32_16x16x32_bf16 v[30:33], v[162:165], v[146:149], v[30:33]
	v_mfma_f32_16x16x32_bf16 v[26:29], v[162:165], v[154:157], v[26:29]
	v_mfma_f32_16x16x32_bf16 v[22:25], v[170:173], v[146:149], v[22:25]
	v_mfma_f32_16x16x32_bf16 v[18:21], v[170:173], v[154:157], v[18:21]
	v_mfma_f32_16x16x32_bf16 v[14:17], v[178:181], v[146:149], v[14:17]
	v_mfma_f32_16x16x32_bf16 v[10:13], v[178:181], v[154:157], v[10:13]
	v_mfma_f32_16x16x32_bf16 v[6:9], v[186:189], v[146:149], v[6:9]
	v_mfma_f32_16x16x32_bf16 v[2:5], v[186:189], v[154:157], v[2:5]
	s_setprio 0
	s_barrier
	ds_read_b128 v[190:193], v137 offset:16384
	ds_read_b128 v[194:197], v137 offset:17408
	ds_read_b128 v[198:201], v137 offset:18432
	ds_read_b128 v[202:205], v137 offset:19456
	s_barrier
	s_waitcnt lgkmcnt(0)
	s_setprio 3
	s_waitcnt lgkmcnt(0)
	v_mfma_f32_16x16x32_bf16 v[62:65], v[158:161], v[190:193], v[62:65]
	v_mfma_f32_16x16x32_bf16 v[58:61], v[158:161], v[198:201], v[58:61]
	v_mfma_f32_16x16x32_bf16 v[54:57], v[166:169], v[190:193], v[54:57]
	v_mfma_f32_16x16x32_bf16 v[50:53], v[166:169], v[198:201], v[50:53]
	v_mfma_f32_16x16x32_bf16 v[46:49], v[174:177], v[190:193], v[46:49]
	v_mfma_f32_16x16x32_bf16 v[42:45], v[174:177], v[198:201], v[42:45]
	v_mfma_f32_16x16x32_bf16 v[38:41], v[182:185], v[190:193], v[38:41]
	v_mfma_f32_16x16x32_bf16 v[34:37], v[182:185], v[198:201], v[34:37]
	v_mfma_f32_16x16x32_bf16 v[62:65], v[162:165], v[194:197], v[62:65]
	v_mfma_f32_16x16x32_bf16 v[58:61], v[162:165], v[202:205], v[58:61]
	v_mfma_f32_16x16x32_bf16 v[54:57], v[170:173], v[194:197], v[54:57]
	v_mfma_f32_16x16x32_bf16 v[50:53], v[170:173], v[202:205], v[50:53]
	v_mfma_f32_16x16x32_bf16 v[46:49], v[178:181], v[194:197], v[46:49]
	v_mfma_f32_16x16x32_bf16 v[42:45], v[178:181], v[202:205], v[42:45]
	v_mfma_f32_16x16x32_bf16 v[38:41], v[186:189], v[194:197], v[38:41]
	v_mfma_f32_16x16x32_bf16 v[34:37], v[186:189], v[202:205], v[34:37]
	s_setprio 0
	s_barrier
	ds_read_b128 v[158:161], v136 offset:16384
	ds_read_b128 v[162:165], v136 offset:17408
	ds_read_b128 v[166:169], v136 offset:18432
	ds_read_b128 v[170:173], v136 offset:19456
	ds_read_b128 v[174:177], v136 offset:20480
	ds_read_b128 v[178:181], v136 offset:21504
	ds_read_b128 v[182:185], v136 offset:22528
	ds_read_b128 v[186:189], v136 offset:23552
	s_waitcnt vmcnt(4)
	s_barrier
	s_waitcnt lgkmcnt(0)
	s_setprio 3
	s_waitcnt lgkmcnt(0)
	v_mfma_f32_16x16x32_bf16 v[94:97], v[158:161], v[142:145], v[94:97]
	v_mfma_f32_16x16x32_bf16 v[90:93], v[158:161], v[150:153], v[90:93]
	v_mfma_f32_16x16x32_bf16 v[86:89], v[166:169], v[142:145], v[86:89]
	v_mfma_f32_16x16x32_bf16 v[82:85], v[166:169], v[150:153], v[82:85]
	v_mfma_f32_16x16x32_bf16 v[78:81], v[174:177], v[142:145], v[78:81]
	v_mfma_f32_16x16x32_bf16 v[74:77], v[174:177], v[150:153], v[74:77]
	v_mfma_f32_16x16x32_bf16 v[70:73], v[182:185], v[142:145], v[70:73]
	v_mfma_f32_16x16x32_bf16 v[66:69], v[182:185], v[150:153], v[66:69]
	v_mfma_f32_16x16x32_bf16 v[216:219], v[162:165], v[146:149], v[94:97]
	v_mfma_f32_16x16x32_bf16 v[220:223], v[162:165], v[154:157], v[90:93]
	v_mfma_f32_16x16x32_bf16 v[224:227], v[170:173], v[146:149], v[86:89]
	v_mfma_f32_16x16x32_bf16 v[228:231], v[170:173], v[154:157], v[82:85]
	v_mfma_f32_16x16x32_bf16 v[232:235], v[178:181], v[146:149], v[78:81]
	v_mfma_f32_16x16x32_bf16 v[236:239], v[178:181], v[154:157], v[74:77]
	v_mfma_f32_16x16x32_bf16 v[142:145], v[186:189], v[146:149], v[70:73]
	v_mfma_f32_16x16x32_bf16 v[146:149], v[186:189], v[154:157], v[66:69]
	s_setprio 0
	s_setprio 3
	v_mfma_f32_16x16x32_bf16 v[66:69], v[158:161], v[190:193], v[126:129]
	v_mfma_f32_16x16x32_bf16 v[150:153], v[162:165], v[194:197], v[66:69]
	v_mfma_f32_16x16x32_bf16 v[66:69], v[158:161], v[198:201], v[122:125]
	v_mfma_f32_16x16x32_bf16 v[154:157], v[162:165], v[202:205], v[66:69]
	v_mfma_f32_16x16x32_bf16 v[66:69], v[166:169], v[190:193], v[118:121]
	v_mfma_f32_16x16x32_bf16 v[158:161], v[170:173], v[194:197], v[66:69]
	v_mfma_f32_16x16x32_bf16 v[66:69], v[166:169], v[198:201], v[114:117]
	v_mfma_f32_16x16x32_bf16 v[162:165], v[170:173], v[202:205], v[66:69]
	v_mfma_f32_16x16x32_bf16 v[66:69], v[174:177], v[190:193], v[110:113]
	v_mfma_f32_16x16x32_bf16 v[166:169], v[178:181], v[194:197], v[66:69]
	v_mfma_f32_16x16x32_bf16 v[66:69], v[174:177], v[198:201], v[106:109]
	v_mfma_f32_16x16x32_bf16 v[170:173], v[178:181], v[202:205], v[66:69]
	v_mfma_f32_16x16x32_bf16 v[66:69], v[182:185], v[190:193], v[102:105]
	v_mfma_f32_16x16x32_bf16 v[174:177], v[186:189], v[194:197], v[66:69]
	v_mfma_f32_16x16x32_bf16 v[66:69], v[182:185], v[198:201], v[98:101]
	v_mfma_f32_16x16x32_bf16 v[178:181], v[186:189], v[202:205], v[66:69]
	s_setprio 0
	s_barrier
	ds_read_b128 v[182:185], v137 offset:32768
	ds_read_b128 v[186:189], v137 offset:33792
	ds_read_b128 v[190:193], v137 offset:34816
	ds_read_b128 v[194:197], v137 offset:35840
	ds_read_b128 v[74:77], v136 offset:32768
	ds_read_b128 v[78:81], v136 offset:33792
	ds_read_b128 v[90:93], v136 offset:34816
	ds_read_b128 v[94:97], v136 offset:35840
	ds_read_b128 v[198:201], v136 offset:36864
	ds_read_b128 v[202:205], v136 offset:37888
	ds_read_b128 v[240:243], v136 offset:38912
	ds_read_b128 v[244:247], v136 offset:39936
	s_waitcnt vmcnt(2)
	s_barrier
	s_waitcnt lgkmcnt(0)
	s_setprio 3
	s_waitcnt lgkmcnt(0)
	v_mfma_f32_16x16x32_bf16 v[30:33], v[74:77], v[182:185], v[30:33]
	v_mfma_f32_16x16x32_bf16 v[26:29], v[74:77], v[190:193], v[26:29]
	v_mfma_f32_16x16x32_bf16 v[22:25], v[90:93], v[182:185], v[22:25]
	v_mfma_f32_16x16x32_bf16 v[18:21], v[90:93], v[190:193], v[18:21]
	v_mfma_f32_16x16x32_bf16 v[14:17], v[198:201], v[182:185], v[14:17]
	v_mfma_f32_16x16x32_bf16 v[10:13], v[198:201], v[190:193], v[10:13]
	v_mfma_f32_16x16x32_bf16 v[6:9], v[240:243], v[182:185], v[6:9]
	v_mfma_f32_16x16x32_bf16 v[2:5], v[240:243], v[190:193], v[2:5]
	v_mfma_f32_16x16x32_bf16 v[118:121], v[78:81], v[186:189], v[30:33]
	v_mfma_f32_16x16x32_bf16 v[114:117], v[78:81], v[194:197], v[26:29]
	v_mfma_f32_16x16x32_bf16 v[102:105], v[94:97], v[186:189], v[22:25]
	v_mfma_f32_16x16x32_bf16 v[98:101], v[94:97], v[194:197], v[18:21]
	v_mfma_f32_16x16x32_bf16 v[86:89], v[202:205], v[186:189], v[14:17]
	v_mfma_f32_16x16x32_bf16 v[82:85], v[202:205], v[194:197], v[10:13]
	v_mfma_f32_16x16x32_bf16 v[70:73], v[244:247], v[186:189], v[6:9]
	v_mfma_f32_16x16x32_bf16 v[66:69], v[244:247], v[194:197], v[2:5]
	s_setprio 0
	s_barrier
	ds_read_b128 v[10:13], v137 offset:49152
	ds_read_b128 v[14:17], v137 offset:50176
	ds_read_b128 v[248:251], v137 offset:51200
	ds_read_b128 v[138:141], v137 offset:52224
	s_waitcnt vmcnt(0)
	s_barrier
	s_waitcnt lgkmcnt(0)
	s_setprio 3
	s_waitcnt lgkmcnt(0)
	v_mfma_f32_16x16x32_bf16 v[2:5], v[74:77], v[10:13], v[62:65]
	v_mfma_f32_16x16x32_bf16 v[126:129], v[78:81], v[14:17], v[2:5]
	v_mfma_f32_16x16x32_bf16 v[2:5], v[74:77], v[248:251], v[58:61]
	v_mfma_f32_16x16x32_bf16 v[122:125], v[78:81], v[138:141], v[2:5]
	v_mfma_f32_16x16x32_bf16 v[2:5], v[90:93], v[10:13], v[54:57]
	v_mfma_f32_16x16x32_bf16 v[110:113], v[94:97], v[14:17], v[2:5]
	v_mfma_f32_16x16x32_bf16 v[2:5], v[90:93], v[248:251], v[50:53]
	v_mfma_f32_16x16x32_bf16 v[106:109], v[94:97], v[138:141], v[2:5]
	v_mfma_f32_16x16x32_bf16 v[2:5], v[198:201], v[10:13], v[46:49]
	v_mfma_f32_16x16x32_bf16 v[94:97], v[202:205], v[14:17], v[2:5]
	v_mfma_f32_16x16x32_bf16 v[2:5], v[198:201], v[248:251], v[42:45]
	v_mfma_f32_16x16x32_bf16 v[90:93], v[202:205], v[138:141], v[2:5]
	v_mfma_f32_16x16x32_bf16 v[2:5], v[240:243], v[10:13], v[38:41]
	v_mfma_f32_16x16x32_bf16 v[78:81], v[244:247], v[14:17], v[2:5]
	v_mfma_f32_16x16x32_bf16 v[2:5], v[240:243], v[248:251], v[34:37]
	v_mfma_f32_16x16x32_bf16 v[74:77], v[244:247], v[138:141], v[2:5]
	s_setprio 0
	s_barrier
	ds_read_b128 v[26:29], v136 offset:49152
	ds_read_b128 v[30:33], v136 offset:50176
	ds_read_b128 v[42:45], v136 offset:51200
	ds_read_b128 v[198:201], v136 offset:52224
	ds_read_b128 v[202:205], v136 offset:53248
	ds_read_b128 v[240:243], v136 offset:54272
	ds_read_b128 v[244:247], v136 offset:55296
	ds_read_b128 v[212:215], v136 offset:56320
	s_barrier
	s_waitcnt lgkmcnt(0)
	s_setprio 3
	s_waitcnt lgkmcnt(0)
	v_mfma_f32_16x16x32_bf16 v[2:5], v[26:29], v[182:185], v[216:219]
	v_mfma_f32_16x16x32_bf16 v[54:57], v[30:33], v[186:189], v[2:5]
	v_mfma_f32_16x16x32_bf16 v[2:5], v[26:29], v[190:193], v[220:223]
	v_mfma_f32_16x16x32_bf16 v[50:53], v[30:33], v[194:197], v[2:5]
	v_mfma_f32_16x16x32_bf16 v[2:5], v[42:45], v[182:185], v[224:227]
	v_mfma_f32_16x16x32_bf16 v[38:41], v[198:201], v[186:189], v[2:5]
	v_mfma_f32_16x16x32_bf16 v[2:5], v[42:45], v[190:193], v[228:231]
	v_mfma_f32_16x16x32_bf16 v[34:37], v[198:201], v[194:197], v[2:5]
	v_mfma_f32_16x16x32_bf16 v[2:5], v[202:205], v[182:185], v[232:235]
	v_mfma_f32_16x16x32_bf16 v[22:25], v[240:243], v[186:189], v[2:5]
	v_mfma_f32_16x16x32_bf16 v[2:5], v[202:205], v[190:193], v[236:239]
	v_mfma_f32_16x16x32_bf16 v[18:21], v[240:243], v[194:197], v[2:5]
	v_mfma_f32_16x16x32_bf16 v[2:5], v[244:247], v[182:185], v[142:145]
	v_mfma_f32_16x16x32_bf16 v[6:9], v[212:215], v[186:189], v[2:5]
	v_mfma_f32_16x16x32_bf16 v[2:5], v[244:247], v[190:193], v[146:149]
	v_mfma_f32_16x16x32_bf16 v[2:5], v[212:215], v[194:197], v[2:5]
	s_setprio 0
	s_setprio 3
	v_mfma_f32_16x16x32_bf16 v[46:49], v[26:29], v[10:13], v[150:153]
	v_mfma_f32_16x16x32_bf16 v[26:29], v[26:29], v[248:251], v[154:157]
	v_mfma_f32_16x16x32_bf16 v[58:61], v[30:33], v[138:141], v[26:29]
	v_mfma_f32_16x16x32_bf16 v[26:29], v[42:45], v[10:13], v[158:161]
	v_mfma_f32_16x16x32_bf16 v[62:65], v[30:33], v[14:17], v[46:49]
	v_mfma_f32_16x16x32_bf16 v[46:49], v[198:201], v[14:17], v[26:29]
	v_mfma_f32_16x16x32_bf16 v[26:29], v[42:45], v[248:251], v[162:165]
	v_mfma_f32_16x16x32_bf16 v[42:45], v[198:201], v[138:141], v[26:29]
	v_mfma_f32_16x16x32_bf16 v[26:29], v[202:205], v[10:13], v[166:169]
	v_mfma_f32_16x16x32_bf16 v[10:13], v[244:247], v[10:13], v[174:177]
	v_mfma_f32_16x16x32_bf16 v[30:33], v[240:243], v[14:17], v[26:29]
	v_mfma_f32_16x16x32_bf16 v[26:29], v[202:205], v[248:251], v[170:173]
	v_mfma_f32_16x16x32_bf16 v[14:17], v[212:215], v[14:17], v[10:13]
	v_mfma_f32_16x16x32_bf16 v[10:13], v[244:247], v[248:251], v[178:181]
	v_mfma_f32_16x16x32_bf16 v[26:29], v[240:243], v[138:141], v[26:29]
	v_mfma_f32_16x16x32_bf16 v[10:13], v[212:215], v[138:141], v[10:13]
	s_setprio 0
	s_and_b64 vcc, exec, s[10:11]
	s_barrier
	s_cbranch_vccz .LBB0_471
	s_barrier
